# v108 + redundant post-barrier lgkmcnt(0) deleted in K-loops
# speedup vs baseline: 1.0006x; 1.0006x over previous
.LBB0_132:
	s_add_u32 s36, s34, 0xfff00080
	s_addc_u32 s37, s35, -1
	s_add_i32 s68, 0, 0x10000
	s_cmp_eq_u32 s67, 60
	s_cselect_b32 s41, s25, s37
	s_cselect_b32 s40, s61, s36
	v_add_u32_e32 v144, s68, v147
	s_cselect_b32 s37, s23, s66
	s_cselect_b32 s36, s62, s63
	s_add_i32 s70, 0, 0x14000
	s_waitcnt lgkmcnt(0)
	ds_read_b128 v[152:155], v144
	ds_read_b128 v[156:159], v144 offset:1024
	ds_read_b128 v[160:163], v144 offset:2048
	ds_read_b128 v[164:167], v144 offset:3072
	v_add_u32_e32 v144, s70, v147
	ds_read_b128 v[168:171], v144
	ds_read_b128 v[172:175], v144 offset:1024
	ds_read_b128 v[176:179], v144 offset:2048
	ds_read_b128 v[180:183], v144 offset:3072
	v_lshl_add_u64 v[212:213], s[34:35], 0, v[140:141]
	s_add_i32 m0, s51, 0xc000
	ds_read_b128 v[184:187], v151
	ds_read_b128 v[188:191], v151 offset:1024
	ds_read_b128 v[192:195], v151 offset:2048
	ds_read_b128 v[196:199], v151 offset:3072
	ds_read_b128 v[200:203], v151 offset:4096
	ds_read_b128 v[204:207], v151 offset:5120
	ds_read_b128 v[208:211], v151 offset:6144
	ds_read_b128 v[216:219], v151 offset:7168
	global_load_lds_dwordx4 v[212:213], off
	v_lshl_add_u64 v[212:213], s[34:35], 0, v[142:143]
	s_add_i32 m0, s51, 0xe000
	s_nop 0
	global_load_lds_dwordx4 v[212:213], off
	s_waitcnt vmcnt(8)
	s_waitcnt lgkmcnt(0)
	s_barrier
	v_mfma_f32_16x16x32_bf16 v[82:85], v[152:155], v[184:187], v[82:85]
	v_mfma_f32_16x16x32_bf16 v[74:77], v[160:163], v[184:187], v[74:77]
	v_mfma_f32_16x16x32_bf16 v[70:73], v[152:155], v[192:195], v[70:73]
	v_mfma_f32_16x16x32_bf16 v[62:65], v[160:163], v[192:195], v[62:65]
	v_mfma_f32_16x16x32_bf16 v[54:57], v[152:155], v[200:203], v[54:57]
	v_mfma_f32_16x16x32_bf16 v[50:53], v[160:163], v[200:203], v[50:53]
	v_mfma_f32_16x16x32_bf16 v[38:41], v[152:155], v[208:211], v[38:41]
	v_mfma_f32_16x16x32_bf16 v[34:37], v[160:163], v[208:211], v[34:37]
	v_mfma_f32_16x16x32_bf16 v[82:85], v[156:159], v[188:191], v[82:85]
	v_mfma_f32_16x16x32_bf16 v[74:77], v[164:167], v[188:191], v[74:77]
	v_mfma_f32_16x16x32_bf16 v[70:73], v[156:159], v[196:199], v[70:73]
	v_mfma_f32_16x16x32_bf16 v[62:65], v[164:167], v[196:199], v[62:65]
	v_mfma_f32_16x16x32_bf16 v[54:57], v[156:159], v[204:207], v[54:57]
	v_mfma_f32_16x16x32_bf16 v[50:53], v[164:167], v[204:207], v[50:53]
	v_mfma_f32_16x16x32_bf16 v[38:41], v[156:159], v[216:219], v[38:41]
	v_mfma_f32_16x16x32_bf16 v[34:37], v[164:167], v[216:219], v[34:37]
	v_mfma_f32_16x16x32_bf16 v[126:129], v[168:171], v[184:187], v[126:129]
	v_mfma_f32_16x16x32_bf16 v[122:125], v[176:179], v[184:187], v[122:125]
	v_mfma_f32_16x16x32_bf16 v[118:121], v[168:171], v[192:195], v[118:121]
	v_mfma_f32_16x16x32_bf16 v[114:117], v[176:179], v[192:195], v[114:117]
	v_mfma_f32_16x16x32_bf16 v[110:113], v[168:171], v[200:203], v[110:113]
	v_mfma_f32_16x16x32_bf16 v[106:109], v[176:179], v[200:203], v[106:109]
	v_mfma_f32_16x16x32_bf16 v[102:105], v[168:171], v[208:211], v[102:105]
	v_mfma_f32_16x16x32_bf16 v[98:101], v[176:179], v[208:211], v[98:101]
	v_mfma_f32_16x16x32_bf16 v[126:129], v[172:175], v[188:191], v[126:129]
	v_mfma_f32_16x16x32_bf16 v[122:125], v[180:183], v[188:191], v[122:125]
	v_mfma_f32_16x16x32_bf16 v[118:121], v[172:175], v[196:199], v[118:121]
	v_mfma_f32_16x16x32_bf16 v[114:117], v[180:183], v[196:199], v[114:117]
	v_mfma_f32_16x16x32_bf16 v[110:113], v[172:175], v[204:207], v[110:113]
	v_mfma_f32_16x16x32_bf16 v[106:109], v[180:183], v[204:207], v[106:109]
	v_mfma_f32_16x16x32_bf16 v[102:105], v[172:175], v[216:219], v[102:105]
	v_mfma_f32_16x16x32_bf16 v[98:101], v[180:183], v[216:219], v[98:101]
	s_barrier
	s_add_i32 s68, s68, s50
	v_lshl_add_u64 v[212:213], s[36:37], 0, v[130:131]
	s_mov_b32 m0, s68
	ds_read_b128 v[184:187], v151 offset:16384
	ds_read_b128 v[188:191], v151 offset:17408
	ds_read_b128 v[192:195], v151 offset:18432
	ds_read_b128 v[196:199], v151 offset:19456
	ds_read_b128 v[200:203], v151 offset:20480
	ds_read_b128 v[204:207], v151 offset:21504
	ds_read_b128 v[208:211], v151 offset:22528
	ds_read_b128 v[216:219], v151 offset:23552
	global_load_lds_dwordx4 v[212:213], off
	s_add_i32 m0, s68, 0x2000
	s_add_u32 s68, s36, 0x100000
	v_lshl_add_u64 v[220:221], s[36:37], 0, v[132:133]
	s_addc_u32 s69, s37, 0
	s_add_i32 s70, s70, s50
	global_load_lds_dwordx4 v[220:221], off
	v_lshl_add_u64 v[222:223], s[68:69], 0, v[130:131]
	s_mov_b32 m0, s70
	v_lshl_add_u64 v[224:225], s[40:41], 0, v[134:135]
	global_load_lds_dwordx4 v[222:223], off
	v_lshl_add_u64 v[222:223], s[68:69], 0, v[132:133]
	s_add_i32 m0, s70, 0x2000
	s_nop 0
	global_load_lds_dwordx4 v[222:223], off
	v_lshl_add_u64 v[222:223], s[40:41], 0, v[136:137]
	s_mov_b32 m0, s51
	s_nop 0
	global_load_lds_dwordx4 v[222:223], off
	s_mov_b32 m0, s52
	s_nop 0
	global_load_lds_dwordx4 v[224:225], off
	s_waitcnt vmcnt(8)
	s_waitcnt lgkmcnt(0)
	s_barrier
	v_mfma_f32_16x16x32_bf16 v[30:33], v[152:155], v[184:187], v[30:33]
	v_mfma_f32_16x16x32_bf16 v[26:29], v[160:163], v[184:187], v[26:29]
	v_mfma_f32_16x16x32_bf16 v[22:25], v[152:155], v[192:195], v[22:25]
	v_mfma_f32_16x16x32_bf16 v[18:21], v[160:163], v[192:195], v[18:21]
	v_mfma_f32_16x16x32_bf16 v[14:17], v[152:155], v[200:203], v[14:17]
	v_mfma_f32_16x16x32_bf16 v[10:13], v[160:163], v[200:203], v[10:13]
	v_mfma_f32_16x16x32_bf16 v[6:9], v[152:155], v[208:211], v[6:9]
	v_mfma_f32_16x16x32_bf16 v[2:5], v[160:163], v[208:211], v[2:5]
	v_mfma_f32_16x16x32_bf16 v[30:33], v[156:159], v[188:191], v[30:33]
	v_mfma_f32_16x16x32_bf16 v[26:29], v[164:167], v[188:191], v[26:29]
	v_mfma_f32_16x16x32_bf16 v[22:25], v[156:159], v[196:199], v[22:25]
	v_mfma_f32_16x16x32_bf16 v[18:21], v[164:167], v[196:199], v[18:21]
	v_mfma_f32_16x16x32_bf16 v[14:17], v[156:159], v[204:207], v[14:17]
	v_mfma_f32_16x16x32_bf16 v[10:13], v[164:167], v[204:207], v[10:13]
	v_mfma_f32_16x16x32_bf16 v[6:9], v[156:159], v[216:219], v[6:9]
	v_mfma_f32_16x16x32_bf16 v[2:5], v[164:167], v[216:219], v[2:5]
	v_mfma_f32_16x16x32_bf16 v[94:97], v[168:171], v[184:187], v[94:97]
	v_mfma_f32_16x16x32_bf16 v[90:93], v[176:179], v[184:187], v[90:93]
	v_mfma_f32_16x16x32_bf16 v[86:89], v[168:171], v[192:195], v[86:89]
	v_mfma_f32_16x16x32_bf16 v[78:81], v[176:179], v[192:195], v[78:81]
	v_mfma_f32_16x16x32_bf16 v[66:69], v[168:171], v[200:203], v[66:69]
	v_mfma_f32_16x16x32_bf16 v[58:61], v[176:179], v[200:203], v[58:61]
	v_mfma_f32_16x16x32_bf16 v[46:49], v[168:171], v[208:211], v[46:49]
	v_mfma_f32_16x16x32_bf16 v[42:45], v[176:179], v[208:211], v[42:45]
	v_mfma_f32_16x16x32_bf16 v[94:97], v[172:175], v[188:191], v[94:97]
	v_mfma_f32_16x16x32_bf16 v[90:93], v[180:183], v[188:191], v[90:93]
	v_mfma_f32_16x16x32_bf16 v[86:89], v[172:175], v[196:199], v[86:89]
	v_mfma_f32_16x16x32_bf16 v[78:81], v[180:183], v[196:199], v[78:81]
	v_mfma_f32_16x16x32_bf16 v[66:69], v[172:175], v[204:207], v[66:69]
	v_mfma_f32_16x16x32_bf16 v[58:61], v[180:183], v[204:207], v[58:61]
	v_mfma_f32_16x16x32_bf16 v[46:49], v[172:175], v[216:219], v[46:49]
	v_mfma_f32_16x16x32_bf16 v[42:45], v[180:183], v[216:219], v[42:45]
	s_barrier
	s_add_i32 s68, 0, 0x18000
	v_add_u32_e32 v144, s68, v147
	s_add_i32 s69, 0, 0x1c000
	ds_read_b128 v[152:155], v144
	ds_read_b128 v[156:159], v144 offset:1024
	ds_read_b128 v[160:163], v144 offset:2048
	ds_read_b128 v[164:167], v144 offset:3072
	v_add_u32_e32 v144, s69, v147
	ds_read_b128 v[168:171], v144
	ds_read_b128 v[172:175], v144 offset:1024
	ds_read_b128 v[176:179], v144 offset:2048
	ds_read_b128 v[180:183], v144 offset:3072
	s_add_u32 s40, s40, 0x100000
	s_addc_u32 s41, s41, 0
	s_mov_b32 m0, s53
	v_lshl_add_u64 v[226:227], s[40:41], 0, v[136:137]
	ds_read_b128 v[184:187], v151 offset:32768
	ds_read_b128 v[188:191], v151 offset:33792
	ds_read_b128 v[192:195], v151 offset:34816
	ds_read_b128 v[196:199], v151 offset:35840
	ds_read_b128 v[200:203], v151 offset:36864
	ds_read_b128 v[204:207], v151 offset:37888
	ds_read_b128 v[208:211], v151 offset:38912
	ds_read_b128 v[216:219], v151 offset:39936
	global_load_lds_dwordx4 v[226:227], off
	v_lshl_add_u64 v[226:227], s[40:41], 0, v[134:135]
	s_mov_b32 m0, s54
	s_nop 0
	global_load_lds_dwordx4 v[226:227], off
	s_waitcnt vmcnt(8)
	s_waitcnt lgkmcnt(0)
	s_barrier
	v_mfma_f32_16x16x32_bf16 v[82:85], v[152:155], v[184:187], v[82:85]
	v_mfma_f32_16x16x32_bf16 v[74:77], v[160:163], v[184:187], v[74:77]
	v_mfma_f32_16x16x32_bf16 v[70:73], v[152:155], v[192:195], v[70:73]
	v_mfma_f32_16x16x32_bf16 v[62:65], v[160:163], v[192:195], v[62:65]
	v_mfma_f32_16x16x32_bf16 v[54:57], v[152:155], v[200:203], v[54:57]
	v_mfma_f32_16x16x32_bf16 v[50:53], v[160:163], v[200:203], v[50:53]
	v_mfma_f32_16x16x32_bf16 v[38:41], v[152:155], v[208:211], v[38:41]
	v_mfma_f32_16x16x32_bf16 v[34:37], v[160:163], v[208:211], v[34:37]
	v_mfma_f32_16x16x32_bf16 v[82:85], v[156:159], v[188:191], v[82:85]
	v_mfma_f32_16x16x32_bf16 v[74:77], v[164:167], v[188:191], v[74:77]
	v_mfma_f32_16x16x32_bf16 v[70:73], v[156:159], v[196:199], v[70:73]
	v_mfma_f32_16x16x32_bf16 v[62:65], v[164:167], v[196:199], v[62:65]
	v_mfma_f32_16x16x32_bf16 v[54:57], v[156:159], v[204:207], v[54:57]
	v_mfma_f32_16x16x32_bf16 v[50:53], v[164:167], v[204:207], v[50:53]
	v_mfma_f32_16x16x32_bf16 v[38:41], v[156:159], v[216:219], v[38:41]
	v_mfma_f32_16x16x32_bf16 v[34:37], v[164:167], v[216:219], v[34:37]
	v_mfma_f32_16x16x32_bf16 v[126:129], v[168:171], v[184:187], v[126:129]
	v_mfma_f32_16x16x32_bf16 v[122:125], v[176:179], v[184:187], v[122:125]
	v_mfma_f32_16x16x32_bf16 v[118:121], v[168:171], v[192:195], v[118:121]
	v_mfma_f32_16x16x32_bf16 v[114:117], v[176:179], v[192:195], v[114:117]
	v_mfma_f32_16x16x32_bf16 v[110:113], v[168:171], v[200:203], v[110:113]
	v_mfma_f32_16x16x32_bf16 v[106:109], v[176:179], v[200:203], v[106:109]
	v_mfma_f32_16x16x32_bf16 v[102:105], v[168:171], v[208:211], v[102:105]
	v_mfma_f32_16x16x32_bf16 v[98:101], v[176:179], v[208:211], v[98:101]
	v_mfma_f32_16x16x32_bf16 v[126:129], v[172:175], v[188:191], v[126:129]
	v_mfma_f32_16x16x32_bf16 v[122:125], v[180:183], v[188:191], v[122:125]
	v_mfma_f32_16x16x32_bf16 v[118:121], v[172:175], v[196:199], v[118:121]
	v_mfma_f32_16x16x32_bf16 v[114:117], v[180:183], v[196:199], v[114:117]
	v_mfma_f32_16x16x32_bf16 v[110:113], v[172:175], v[204:207], v[110:113]
	v_mfma_f32_16x16x32_bf16 v[106:109], v[180:183], v[204:207], v[106:109]
	v_mfma_f32_16x16x32_bf16 v[102:105], v[172:175], v[216:219], v[102:105]
	v_mfma_f32_16x16x32_bf16 v[98:101], v[180:183], v[216:219], v[98:101]
	s_barrier
	s_add_i32 s40, s68, s50
	v_lshl_add_u64 v[212:213], v[212:213], 0, s[18:19]
	s_mov_b32 m0, s40
	ds_read_b128 v[184:187], v151 offset:49152
	ds_read_b128 v[188:191], v151 offset:50176
	ds_read_b128 v[192:195], v151 offset:51200
	ds_read_b128 v[196:199], v151 offset:52224
	ds_read_b128 v[200:203], v151 offset:53248
	ds_read_b128 v[204:207], v151 offset:54272
	ds_read_b128 v[208:211], v151 offset:55296
	ds_read_b128 v[216:219], v151 offset:56320
	global_load_lds_dwordx4 v[212:213], off
	s_add_i32 m0, s40, 0x2000
	s_add_u32 s36, s36, 0x100080
	v_lshl_add_u64 v[212:213], v[220:221], 0, s[18:19]
	s_addc_u32 s37, s37, 0
	s_add_i32 s40, s69, s50
	global_load_lds_dwordx4 v[212:213], off
	v_lshl_add_u64 v[212:213], s[36:37], 0, v[130:131]
	s_mov_b32 m0, s40
	s_nop 0
	global_load_lds_dwordx4 v[212:213], off
	v_lshl_add_u64 v[212:213], s[36:37], 0, v[132:133]
	s_add_i32 m0, s40, 0x2000
	s_nop 0
	global_load_lds_dwordx4 v[212:213], off
	v_lshl_add_u64 v[212:213], v[222:223], 0, s[18:19]
	s_mov_b32 m0, s30
	s_nop 0
	global_load_lds_dwordx4 v[212:213], off
	v_lshl_add_u64 v[212:213], v[224:225], 0, s[18:19]
	s_mov_b32 m0, s55
	s_nop 0
	global_load_lds_dwordx4 v[212:213], off
	s_waitcnt vmcnt(8)
	s_waitcnt lgkmcnt(0)
	s_barrier
	v_mfma_f32_16x16x32_bf16 v[30:33], v[152:155], v[184:187], v[30:33]
	v_mfma_f32_16x16x32_bf16 v[26:29], v[160:163], v[184:187], v[26:29]
	v_mfma_f32_16x16x32_bf16 v[22:25], v[152:155], v[192:195], v[22:25]
	v_mfma_f32_16x16x32_bf16 v[18:21], v[160:163], v[192:195], v[18:21]
	v_mfma_f32_16x16x32_bf16 v[14:17], v[152:155], v[200:203], v[14:17]
	v_mfma_f32_16x16x32_bf16 v[10:13], v[160:163], v[200:203], v[10:13]
	v_mfma_f32_16x16x32_bf16 v[6:9], v[152:155], v[208:211], v[6:9]
	v_mfma_f32_16x16x32_bf16 v[2:5], v[160:163], v[208:211], v[2:5]
	v_mfma_f32_16x16x32_bf16 v[30:33], v[156:159], v[188:191], v[30:33]
	v_mfma_f32_16x16x32_bf16 v[26:29], v[164:167], v[188:191], v[26:29]
	v_mfma_f32_16x16x32_bf16 v[22:25], v[156:159], v[196:199], v[22:25]
	v_mfma_f32_16x16x32_bf16 v[18:21], v[164:167], v[196:199], v[18:21]
	v_mfma_f32_16x16x32_bf16 v[14:17], v[156:159], v[204:207], v[14:17]
	v_mfma_f32_16x16x32_bf16 v[10:13], v[164:167], v[204:207], v[10:13]
	v_mfma_f32_16x16x32_bf16 v[6:9], v[156:159], v[216:219], v[6:9]
	v_mfma_f32_16x16x32_bf16 v[2:5], v[164:167], v[216:219], v[2:5]
	v_mfma_f32_16x16x32_bf16 v[94:97], v[168:171], v[184:187], v[94:97]
	v_mfma_f32_16x16x32_bf16 v[90:93], v[176:179], v[184:187], v[90:93]
	v_mfma_f32_16x16x32_bf16 v[86:89], v[168:171], v[192:195], v[86:89]
	v_mfma_f32_16x16x32_bf16 v[78:81], v[176:179], v[192:195], v[78:81]
	v_mfma_f32_16x16x32_bf16 v[66:69], v[168:171], v[200:203], v[66:69]
	v_mfma_f32_16x16x32_bf16 v[58:61], v[176:179], v[200:203], v[58:61]
	v_mfma_f32_16x16x32_bf16 v[46:49], v[168:171], v[208:211], v[46:49]
	v_mfma_f32_16x16x32_bf16 v[42:45], v[176:179], v[208:211], v[42:45]
	v_mfma_f32_16x16x32_bf16 v[94:97], v[172:175], v[188:191], v[94:97]
	v_mfma_f32_16x16x32_bf16 v[90:93], v[180:183], v[188:191], v[90:93]
	v_mfma_f32_16x16x32_bf16 v[86:89], v[172:175], v[196:199], v[86:89]
	v_mfma_f32_16x16x32_bf16 v[78:81], v[180:183], v[196:199], v[78:81]
	v_mfma_f32_16x16x32_bf16 v[66:69], v[172:175], v[204:207], v[66:69]
	v_mfma_f32_16x16x32_bf16 v[58:61], v[180:183], v[204:207], v[58:61]
	v_mfma_f32_16x16x32_bf16 v[46:49], v[172:175], v[216:219], v[46:49]
	v_mfma_f32_16x16x32_bf16 v[42:45], v[180:183], v[216:219], v[42:45]
	s_barrier
	s_add_i32 s67, s67, 2
	s_add_u32 s34, s34, 0x100
	s_addc_u32 s35, s35, 0
	s_add_u32 s63, s63, 0x100
	s_addc_u32 s66, s66, 0
	s_cmp_gt_u32 s67, 61
	s_cbranch_scc0 .LBB0_132
	s_and_b64 vcc, exec, s[12:13]
	s_cbranch_vccz .LBB0_135
	s_barrier

.LBB0_872:
	s_add_u32 s26, s24, 0xfff00080
	s_addc_u32 s27, s25, -1
	s_add_i32 s56, 0, 0x10000
	s_cmp_eq_u32 s55, 60
	s_cselect_b32 s29, s13, s27
	s_cselect_b32 s28, s51, s26
	v_add_u32_e32 v148, s56, v152
	s_cselect_b32 s27, s9, s54
	s_cselect_b32 s26, s52, s53
	s_add_i32 s58, 0, 0x14000
	ds_read_b128 v[144:147], v148
	ds_read_b128 v[156:159], v148 offset:1024
	ds_read_b128 v[160:163], v148 offset:2048
	ds_read_b128 v[164:167], v148 offset:3072
	v_add_u32_e32 v148, s58, v152
	ds_read_b128 v[168:171], v148
	ds_read_b128 v[172:175], v148 offset:1024
	ds_read_b128 v[176:179], v148 offset:2048
	ds_read_b128 v[180:183], v148 offset:3072
	v_lshl_add_u64 v[148:149], s[24:25], 0, v[140:141]
	s_add_i32 m0, s41, 0xc000
	ds_read_b128 v[184:187], v154
	ds_read_b128 v[188:191], v154 offset:1024
	ds_read_b128 v[192:195], v154 offset:2048
	ds_read_b128 v[196:199], v154 offset:3072
	ds_read_b128 v[200:203], v154 offset:4096
	ds_read_b128 v[204:207], v154 offset:5120
	ds_read_b128 v[208:211], v154 offset:6144
	ds_read_b128 v[216:219], v154 offset:7168
	global_load_lds_dwordx4 v[148:149], off
	v_lshl_add_u64 v[148:149], s[24:25], 0, v[142:143]
	s_add_i32 m0, s41, 0xe000
	s_nop 0
	global_load_lds_dwordx4 v[148:149], off
	s_waitcnt vmcnt(8)
	s_waitcnt lgkmcnt(0)
	s_barrier
	v_mfma_f32_16x16x32_bf16 v[126:129], v[144:147], v[184:187], v[126:129]
	v_mfma_f32_16x16x32_bf16 v[122:125], v[160:163], v[184:187], v[122:125]
	v_mfma_f32_16x16x32_bf16 v[110:113], v[144:147], v[192:195], v[110:113]
	v_mfma_f32_16x16x32_bf16 v[106:109], v[160:163], v[192:195], v[106:109]
	v_mfma_f32_16x16x32_bf16 v[94:97], v[144:147], v[200:203], v[94:97]
	v_mfma_f32_16x16x32_bf16 v[90:93], v[160:163], v[200:203], v[90:93]
	v_mfma_f32_16x16x32_bf16 v[78:81], v[144:147], v[208:211], v[78:81]
	v_mfma_f32_16x16x32_bf16 v[74:77], v[160:163], v[208:211], v[74:77]
	v_mfma_f32_16x16x32_bf16 v[126:129], v[156:159], v[188:191], v[126:129]
	v_mfma_f32_16x16x32_bf16 v[122:125], v[164:167], v[188:191], v[122:125]
	v_mfma_f32_16x16x32_bf16 v[110:113], v[156:159], v[196:199], v[110:113]
	v_mfma_f32_16x16x32_bf16 v[106:109], v[164:167], v[196:199], v[106:109]
	v_mfma_f32_16x16x32_bf16 v[94:97], v[156:159], v[204:207], v[94:97]
	v_mfma_f32_16x16x32_bf16 v[90:93], v[164:167], v[204:207], v[90:93]
	v_mfma_f32_16x16x32_bf16 v[78:81], v[156:159], v[216:219], v[78:81]
	v_mfma_f32_16x16x32_bf16 v[74:77], v[164:167], v[216:219], v[74:77]
	v_mfma_f32_16x16x32_bf16 v[118:121], v[168:171], v[184:187], v[118:121]
	v_mfma_f32_16x16x32_bf16 v[114:117], v[176:179], v[184:187], v[114:117]
	v_mfma_f32_16x16x32_bf16 v[102:105], v[168:171], v[192:195], v[102:105]
	v_mfma_f32_16x16x32_bf16 v[98:101], v[176:179], v[192:195], v[98:101]
	v_mfma_f32_16x16x32_bf16 v[86:89], v[168:171], v[200:203], v[86:89]
	v_mfma_f32_16x16x32_bf16 v[82:85], v[176:179], v[200:203], v[82:85]
	v_mfma_f32_16x16x32_bf16 v[70:73], v[168:171], v[208:211], v[70:73]
	v_mfma_f32_16x16x32_bf16 v[66:69], v[176:179], v[208:211], v[66:69]
	v_mfma_f32_16x16x32_bf16 v[118:121], v[172:175], v[188:191], v[118:121]
	v_mfma_f32_16x16x32_bf16 v[114:117], v[180:183], v[188:191], v[114:117]
	v_mfma_f32_16x16x32_bf16 v[102:105], v[172:175], v[196:199], v[102:105]
	v_mfma_f32_16x16x32_bf16 v[98:101], v[180:183], v[196:199], v[98:101]
	v_mfma_f32_16x16x32_bf16 v[86:89], v[172:175], v[204:207], v[86:89]
	v_mfma_f32_16x16x32_bf16 v[82:85], v[180:183], v[204:207], v[82:85]
	v_mfma_f32_16x16x32_bf16 v[70:73], v[172:175], v[216:219], v[70:73]
	v_mfma_f32_16x16x32_bf16 v[66:69], v[180:183], v[216:219], v[66:69]
	s_barrier
	s_add_i32 s56, s56, s40
	v_lshl_add_u64 v[148:149], s[26:27], 0, v[130:131]
	s_mov_b32 m0, s56
	ds_read_b128 v[184:187], v154 offset:16384
	ds_read_b128 v[188:191], v154 offset:17408
	ds_read_b128 v[192:195], v154 offset:18432
	ds_read_b128 v[196:199], v154 offset:19456
	ds_read_b128 v[200:203], v154 offset:20480
	ds_read_b128 v[204:207], v154 offset:21504
	ds_read_b128 v[208:211], v154 offset:22528
	ds_read_b128 v[216:219], v154 offset:23552
	global_load_lds_dwordx4 v[148:149], off
	s_add_i32 m0, s56, 0x2000
	s_add_u32 s56, s26, 0x100000
	v_lshl_add_u64 v[212:213], s[26:27], 0, v[132:133]
	s_addc_u32 s57, s27, 0
	s_add_i32 s58, s58, s40
	global_load_lds_dwordx4 v[212:213], off
	v_lshl_add_u64 v[220:221], s[56:57], 0, v[130:131]
	s_mov_b32 m0, s58
	v_lshl_add_u64 v[222:223], s[28:29], 0, v[134:135]
	global_load_lds_dwordx4 v[220:221], off
	v_lshl_add_u64 v[220:221], s[56:57], 0, v[132:133]
	s_add_i32 m0, s58, 0x2000
	s_nop 0
	global_load_lds_dwordx4 v[220:221], off
	v_lshl_add_u64 v[220:221], s[28:29], 0, v[136:137]
	s_mov_b32 m0, s41
	s_nop 0
	global_load_lds_dwordx4 v[220:221], off
	s_mov_b32 m0, s44
	s_nop 0
	global_load_lds_dwordx4 v[222:223], off
	s_waitcnt vmcnt(8)
	s_waitcnt lgkmcnt(0)
	s_barrier
	v_mfma_f32_16x16x32_bf16 v[62:65], v[144:147], v[184:187], v[62:65]
	v_mfma_f32_16x16x32_bf16 v[58:61], v[160:163], v[184:187], v[58:61]
	v_mfma_f32_16x16x32_bf16 v[46:49], v[144:147], v[192:195], v[46:49]
	v_mfma_f32_16x16x32_bf16 v[42:45], v[160:163], v[192:195], v[42:45]
	v_mfma_f32_16x16x32_bf16 v[30:33], v[144:147], v[200:203], v[30:33]
	v_mfma_f32_16x16x32_bf16 v[26:29], v[160:163], v[200:203], v[26:29]
	v_mfma_f32_16x16x32_bf16 v[14:17], v[144:147], v[208:211], v[14:17]
	v_mfma_f32_16x16x32_bf16 v[10:13], v[160:163], v[208:211], v[10:13]
	v_mfma_f32_16x16x32_bf16 v[62:65], v[156:159], v[188:191], v[62:65]
	v_mfma_f32_16x16x32_bf16 v[58:61], v[164:167], v[188:191], v[58:61]
	v_mfma_f32_16x16x32_bf16 v[46:49], v[156:159], v[196:199], v[46:49]
	v_mfma_f32_16x16x32_bf16 v[42:45], v[164:167], v[196:199], v[42:45]
	v_mfma_f32_16x16x32_bf16 v[30:33], v[156:159], v[204:207], v[30:33]
	v_mfma_f32_16x16x32_bf16 v[26:29], v[164:167], v[204:207], v[26:29]
	v_mfma_f32_16x16x32_bf16 v[14:17], v[156:159], v[216:219], v[14:17]
	v_mfma_f32_16x16x32_bf16 v[10:13], v[164:167], v[216:219], v[10:13]
	v_mfma_f32_16x16x32_bf16 v[54:57], v[168:171], v[184:187], v[54:57]
	v_mfma_f32_16x16x32_bf16 v[50:53], v[176:179], v[184:187], v[50:53]
	v_mfma_f32_16x16x32_bf16 v[38:41], v[168:171], v[192:195], v[38:41]
	v_mfma_f32_16x16x32_bf16 v[34:37], v[176:179], v[192:195], v[34:37]
	v_mfma_f32_16x16x32_bf16 v[22:25], v[168:171], v[200:203], v[22:25]
	v_mfma_f32_16x16x32_bf16 v[18:21], v[176:179], v[200:203], v[18:21]
	v_mfma_f32_16x16x32_bf16 v[6:9], v[168:171], v[208:211], v[6:9]
	v_mfma_f32_16x16x32_bf16 v[2:5], v[176:179], v[208:211], v[2:5]
	v_mfma_f32_16x16x32_bf16 v[54:57], v[172:175], v[188:191], v[54:57]
	v_mfma_f32_16x16x32_bf16 v[50:53], v[180:183], v[188:191], v[50:53]
	v_mfma_f32_16x16x32_bf16 v[38:41], v[172:175], v[196:199], v[38:41]
	v_mfma_f32_16x16x32_bf16 v[34:37], v[180:183], v[196:199], v[34:37]
	v_mfma_f32_16x16x32_bf16 v[22:25], v[172:175], v[204:207], v[22:25]
	v_mfma_f32_16x16x32_bf16 v[18:21], v[180:183], v[204:207], v[18:21]
	v_mfma_f32_16x16x32_bf16 v[6:9], v[172:175], v[216:219], v[6:9]
	v_mfma_f32_16x16x32_bf16 v[2:5], v[180:183], v[216:219], v[2:5]
	s_barrier
	s_add_i32 s56, 0, 0x18000
	v_add_u32_e32 v155, s56, v152
	s_add_i32 s57, 0, 0x1c000
	ds_read_b128 v[144:147], v155
	ds_read_b128 v[156:159], v155 offset:1024
	ds_read_b128 v[160:163], v155 offset:2048
	ds_read_b128 v[164:167], v155 offset:3072
	v_add_u32_e32 v155, s57, v152
	ds_read_b128 v[168:171], v155
	ds_read_b128 v[172:175], v155 offset:1024
	ds_read_b128 v[176:179], v155 offset:2048
	ds_read_b128 v[180:183], v155 offset:3072
	s_add_u32 s28, s28, 0x100000
	s_addc_u32 s29, s29, 0
	s_mov_b32 m0, s45
	v_lshl_add_u64 v[224:225], s[28:29], 0, v[136:137]
	ds_read_b128 v[184:187], v154 offset:32768
	ds_read_b128 v[188:191], v154 offset:33792
	ds_read_b128 v[192:195], v154 offset:34816
	ds_read_b128 v[196:199], v154 offset:35840
	ds_read_b128 v[200:203], v154 offset:36864
	ds_read_b128 v[204:207], v154 offset:37888
	ds_read_b128 v[208:211], v154 offset:38912
	ds_read_b128 v[216:219], v154 offset:39936
	global_load_lds_dwordx4 v[224:225], off
	v_lshl_add_u64 v[224:225], s[28:29], 0, v[134:135]
	s_mov_b32 m0, s46
	s_nop 0
	global_load_lds_dwordx4 v[224:225], off
	s_waitcnt vmcnt(8)
	s_waitcnt lgkmcnt(0)
	s_barrier
	v_mfma_f32_16x16x32_bf16 v[126:129], v[144:147], v[184:187], v[126:129]
	v_mfma_f32_16x16x32_bf16 v[122:125], v[160:163], v[184:187], v[122:125]
	v_mfma_f32_16x16x32_bf16 v[110:113], v[144:147], v[192:195], v[110:113]
	v_mfma_f32_16x16x32_bf16 v[106:109], v[160:163], v[192:195], v[106:109]
	v_mfma_f32_16x16x32_bf16 v[94:97], v[144:147], v[200:203], v[94:97]
	v_mfma_f32_16x16x32_bf16 v[90:93], v[160:163], v[200:203], v[90:93]
	v_mfma_f32_16x16x32_bf16 v[78:81], v[144:147], v[208:211], v[78:81]
	v_mfma_f32_16x16x32_bf16 v[74:77], v[160:163], v[208:211], v[74:77]
	v_mfma_f32_16x16x32_bf16 v[126:129], v[156:159], v[188:191], v[126:129]
	v_mfma_f32_16x16x32_bf16 v[122:125], v[164:167], v[188:191], v[122:125]
	v_mfma_f32_16x16x32_bf16 v[110:113], v[156:159], v[196:199], v[110:113]
	v_mfma_f32_16x16x32_bf16 v[106:109], v[164:167], v[196:199], v[106:109]
	v_mfma_f32_16x16x32_bf16 v[94:97], v[156:159], v[204:207], v[94:97]
	v_mfma_f32_16x16x32_bf16 v[90:93], v[164:167], v[204:207], v[90:93]
	v_mfma_f32_16x16x32_bf16 v[78:81], v[156:159], v[216:219], v[78:81]
	v_mfma_f32_16x16x32_bf16 v[74:77], v[164:167], v[216:219], v[74:77]
	v_mfma_f32_16x16x32_bf16 v[118:121], v[168:171], v[184:187], v[118:121]
	v_mfma_f32_16x16x32_bf16 v[114:117], v[176:179], v[184:187], v[114:117]
	v_mfma_f32_16x16x32_bf16 v[102:105], v[168:171], v[192:195], v[102:105]
	v_mfma_f32_16x16x32_bf16 v[98:101], v[176:179], v[192:195], v[98:101]
	v_mfma_f32_16x16x32_bf16 v[86:89], v[168:171], v[200:203], v[86:89]
	v_mfma_f32_16x16x32_bf16 v[82:85], v[176:179], v[200:203], v[82:85]
	v_mfma_f32_16x16x32_bf16 v[70:73], v[168:171], v[208:211], v[70:73]
	v_mfma_f32_16x16x32_bf16 v[66:69], v[176:179], v[208:211], v[66:69]
	v_mfma_f32_16x16x32_bf16 v[118:121], v[172:175], v[188:191], v[118:121]
	v_mfma_f32_16x16x32_bf16 v[114:117], v[180:183], v[188:191], v[114:117]
	v_mfma_f32_16x16x32_bf16 v[102:105], v[172:175], v[196:199], v[102:105]
	v_mfma_f32_16x16x32_bf16 v[98:101], v[180:183], v[196:199], v[98:101]
	v_mfma_f32_16x16x32_bf16 v[86:89], v[172:175], v[204:207], v[86:89]
	v_mfma_f32_16x16x32_bf16 v[82:85], v[180:183], v[204:207], v[82:85]
	v_mfma_f32_16x16x32_bf16 v[70:73], v[172:175], v[216:219], v[70:73]
	v_mfma_f32_16x16x32_bf16 v[66:69], v[180:183], v[216:219], v[66:69]
	s_barrier
	s_add_i32 s28, s56, s40
	v_lshl_add_u64 v[148:149], v[148:149], 0, s[18:19]
	s_mov_b32 m0, s28
	ds_read_b128 v[184:187], v154 offset:49152
	ds_read_b128 v[188:191], v154 offset:50176
	ds_read_b128 v[192:195], v154 offset:51200
	ds_read_b128 v[196:199], v154 offset:52224
	ds_read_b128 v[200:203], v154 offset:53248
	ds_read_b128 v[204:207], v154 offset:54272
	ds_read_b128 v[208:211], v154 offset:55296
	ds_read_b128 v[216:219], v154 offset:56320
	global_load_lds_dwordx4 v[148:149], off
	s_add_i32 m0, s28, 0x2000
	s_add_u32 s26, s26, 0x100080
	v_lshl_add_u64 v[148:149], v[212:213], 0, s[18:19]
	s_addc_u32 s27, s27, 0
	s_add_i32 s28, s57, s40
	global_load_lds_dwordx4 v[148:149], off
	v_lshl_add_u64 v[148:149], s[26:27], 0, v[130:131]
	s_mov_b32 m0, s28
	s_nop 0
	global_load_lds_dwordx4 v[148:149], off
	v_lshl_add_u64 v[148:149], s[26:27], 0, v[132:133]
	s_add_i32 m0, s28, 0x2000
	s_nop 0
	global_load_lds_dwordx4 v[148:149], off
	v_lshl_add_u64 v[148:149], v[220:221], 0, s[18:19]
	s_mov_b32 m0, s30
	s_nop 0
	global_load_lds_dwordx4 v[148:149], off
	v_lshl_add_u64 v[148:149], v[222:223], 0, s[18:19]
	s_mov_b32 m0, s47
	s_nop 0
	global_load_lds_dwordx4 v[148:149], off
	s_waitcnt vmcnt(8)
	s_waitcnt lgkmcnt(0)
	s_barrier
	v_mfma_f32_16x16x32_bf16 v[62:65], v[144:147], v[184:187], v[62:65]
	v_mfma_f32_16x16x32_bf16 v[58:61], v[160:163], v[184:187], v[58:61]
	v_mfma_f32_16x16x32_bf16 v[46:49], v[144:147], v[192:195], v[46:49]
	v_mfma_f32_16x16x32_bf16 v[42:45], v[160:163], v[192:195], v[42:45]
	v_mfma_f32_16x16x32_bf16 v[30:33], v[144:147], v[200:203], v[30:33]
	v_mfma_f32_16x16x32_bf16 v[26:29], v[160:163], v[200:203], v[26:29]
	v_mfma_f32_16x16x32_bf16 v[14:17], v[144:147], v[208:211], v[14:17]
	v_mfma_f32_16x16x32_bf16 v[10:13], v[160:163], v[208:211], v[10:13]
	v_mfma_f32_16x16x32_bf16 v[62:65], v[156:159], v[188:191], v[62:65]
	v_mfma_f32_16x16x32_bf16 v[58:61], v[164:167], v[188:191], v[58:61]
	v_mfma_f32_16x16x32_bf16 v[46:49], v[156:159], v[196:199], v[46:49]
	v_mfma_f32_16x16x32_bf16 v[42:45], v[164:167], v[196:199], v[42:45]
	v_mfma_f32_16x16x32_bf16 v[30:33], v[156:159], v[204:207], v[30:33]
	v_mfma_f32_16x16x32_bf16 v[26:29], v[164:167], v[204:207], v[26:29]
	v_mfma_f32_16x16x32_bf16 v[14:17], v[156:159], v[216:219], v[14:17]
	v_mfma_f32_16x16x32_bf16 v[10:13], v[164:167], v[216:219], v[10:13]
	v_mfma_f32_16x16x32_bf16 v[54:57], v[168:171], v[184:187], v[54:57]
	v_mfma_f32_16x16x32_bf16 v[50:53], v[176:179], v[184:187], v[50:53]
	v_mfma_f32_16x16x32_bf16 v[38:41], v[168:171], v[192:195], v[38:41]
	v_mfma_f32_16x16x32_bf16 v[34:37], v[176:179], v[192:195], v[34:37]
	v_mfma_f32_16x16x32_bf16 v[22:25], v[168:171], v[200:203], v[22:25]
	v_mfma_f32_16x16x32_bf16 v[18:21], v[176:179], v[200:203], v[18:21]
	v_mfma_f32_16x16x32_bf16 v[6:9], v[168:171], v[208:211], v[6:9]
	v_mfma_f32_16x16x32_bf16 v[2:5], v[176:179], v[208:211], v[2:5]
	v_mfma_f32_16x16x32_bf16 v[54:57], v[172:175], v[188:191], v[54:57]
	v_mfma_f32_16x16x32_bf16 v[50:53], v[180:183], v[188:191], v[50:53]
	v_mfma_f32_16x16x32_bf16 v[38:41], v[172:175], v[196:199], v[38:41]
	v_mfma_f32_16x16x32_bf16 v[34:37], v[180:183], v[196:199], v[34:37]
	v_mfma_f32_16x16x32_bf16 v[22:25], v[172:175], v[204:207], v[22:25]
	v_mfma_f32_16x16x32_bf16 v[18:21], v[180:183], v[204:207], v[18:21]
	v_mfma_f32_16x16x32_bf16 v[6:9], v[172:175], v[216:219], v[6:9]
	v_mfma_f32_16x16x32_bf16 v[2:5], v[180:183], v[216:219], v[2:5]
	s_barrier
	s_add_i32 s55, s55, 2
	s_add_u32 s24, s24, 0x100
	s_addc_u32 s25, s25, 0
	s_add_u32 s53, s53, 0x100
	s_addc_u32 s54, s54, 0
	s_cmp_gt_u32 s55, 61
	s_cbranch_scc0 .LBB0_872
	s_and_b64 vcc, exec, s[6:7]
	s_cbranch_vccz .LBB0_875
	s_barrier

.LBB0_1024:
	s_add_u32 s46, s2, 0xfff00080
	s_addc_u32 s47, s3, -1
	s_add_i32 s83, 0, 0x10000
	s_cmp_eq_u32 s82, 60
	s_cselect_b32 s59, s30, s47
	s_cselect_b32 s58, s53, s46
	s_cselect_b32 s47, s51, s81
	s_cselect_b32 s46, s79, s80
	s_add_i32 s86, 0, 0x14000
	v_add_u32_e32 v74, s83, v244
	v_add_u32_e32 v94, s86, v244
	ds_read_b128 v[62:65], v74
	ds_read_b128 v[66:69], v74 offset:1024
	ds_read_b128 v[70:73], v74 offset:2048
	ds_read_b128 v[74:77], v74 offset:3072
	ds_read_b128 v[78:81], v94
	ds_read_b128 v[82:85], v94 offset:1024
	ds_read_b128 v[90:93], v94 offset:2048
	ds_read_b128 v[94:97], v94 offset:3072
	v_lshl_add_u64 v[196:197], s[2:3], 0, v[222:223]
	s_add_i32 m0, s67, 0xc000
	ds_read_b128 v[98:101], v250
	ds_read_b128 v[102:105], v250 offset:1024
	ds_read_b128 v[106:109], v250 offset:2048
	ds_read_b128 v[110:113], v250 offset:3072
	ds_read_b128 v[180:183], v250 offset:4096
	ds_read_b128 v[184:187], v250 offset:5120
	ds_read_b128 v[188:191], v250 offset:6144
	ds_read_b128 v[192:195], v250 offset:7168
	global_load_lds_dwordx4 v[196:197], off
	v_lshl_add_u64 v[196:197], s[2:3], 0, v[224:225]
	s_add_i32 m0, s67, 0xe000
	s_nop 0
	global_load_lds_dwordx4 v[196:197], off
	s_waitcnt vmcnt(8)
	s_waitcnt lgkmcnt(0)
	s_barrier
	v_mfma_f32_16x16x32_bf16 v[176:179], v[62:65], v[98:101], v[176:179]
	v_mfma_f32_16x16x32_bf16 v[168:171], v[70:73], v[98:101], v[168:171]
	v_mfma_f32_16x16x32_bf16 v[160:163], v[62:65], v[106:109], v[160:163]
	v_mfma_f32_16x16x32_bf16 v[152:155], v[70:73], v[106:109], v[152:155]
	v_mfma_f32_16x16x32_bf16 v[144:147], v[62:65], v[180:183], v[144:147]
	v_mfma_f32_16x16x32_bf16 v[136:139], v[70:73], v[180:183], v[136:139]
	v_mfma_f32_16x16x32_bf16 v[126:129], v[62:65], v[188:191], v[126:129]
	v_mfma_f32_16x16x32_bf16 v[118:121], v[70:73], v[188:191], v[118:121]
	v_mfma_f32_16x16x32_bf16 v[176:179], v[66:69], v[102:105], v[176:179]
	v_mfma_f32_16x16x32_bf16 v[168:171], v[74:77], v[102:105], v[168:171]
	v_mfma_f32_16x16x32_bf16 v[160:163], v[66:69], v[110:113], v[160:163]
	v_mfma_f32_16x16x32_bf16 v[152:155], v[74:77], v[110:113], v[152:155]
	v_mfma_f32_16x16x32_bf16 v[144:147], v[66:69], v[184:187], v[144:147]
	v_mfma_f32_16x16x32_bf16 v[136:139], v[74:77], v[184:187], v[136:139]
	v_mfma_f32_16x16x32_bf16 v[126:129], v[66:69], v[192:195], v[126:129]
	v_mfma_f32_16x16x32_bf16 v[118:121], v[74:77], v[192:195], v[118:121]
	v_mfma_f32_16x16x32_bf16 v[172:175], v[78:81], v[98:101], v[172:175]
	v_mfma_f32_16x16x32_bf16 v[98:101], v[90:93], v[98:101], v[164:167]
	v_mfma_f32_16x16x32_bf16 v[172:175], v[82:85], v[102:105], v[172:175]
	v_mfma_f32_16x16x32_bf16 v[98:101], v[94:97], v[102:105], v[98:101]
	v_mfma_f32_16x16x32_bf16 v[102:105], v[78:81], v[106:109], v[156:159]
	v_mfma_f32_16x16x32_bf16 v[106:109], v[90:93], v[106:109], v[148:151]
	v_mfma_f32_16x16x32_bf16 v[132:135], v[90:93], v[180:183], v[132:135]
	v_mfma_f32_16x16x32_bf16 v[122:125], v[78:81], v[188:191], v[122:125]
	v_mfma_f32_16x16x32_bf16 v[114:117], v[90:93], v[188:191], v[114:117]
	v_mfma_f32_16x16x32_bf16 v[102:105], v[82:85], v[110:113], v[102:105]
	v_mfma_f32_16x16x32_bf16 v[106:109], v[94:97], v[110:113], v[106:109]
	v_mfma_f32_16x16x32_bf16 v[110:113], v[78:81], v[180:183], v[140:143]
	v_mfma_f32_16x16x32_bf16 v[132:135], v[94:97], v[184:187], v[132:135]
	v_mfma_f32_16x16x32_bf16 v[122:125], v[82:85], v[192:195], v[122:125]
	v_mfma_f32_16x16x32_bf16 v[114:117], v[94:97], v[192:195], v[114:117]
	v_mfma_f32_16x16x32_bf16 v[110:113], v[82:85], v[184:187], v[110:113]
	s_barrier
	s_add_i32 s83, s83, s66
	v_lshl_add_u64 v[204:205], s[46:47], 0, v[130:131]
	s_mov_b32 m0, s83
	ds_read_b128 v[140:143], v250 offset:16384
	ds_read_b128 v[148:151], v250 offset:17408
	ds_read_b128 v[156:159], v250 offset:18432
	ds_read_b128 v[164:167], v250 offset:19456
	ds_read_b128 v[180:183], v250 offset:20480
	ds_read_b128 v[184:187], v250 offset:21504
	ds_read_b128 v[188:191], v250 offset:22528
	ds_read_b128 v[192:195], v250 offset:23552
	global_load_lds_dwordx4 v[204:205], off
	s_add_i32 m0, s83, 0x2000
	s_add_u32 s84, s46, 0x100000
	v_lshl_add_u64 v[206:207], s[46:47], 0, v[216:217]
	s_addc_u32 s85, s47, 0
	s_add_i32 s83, s86, s66
	global_load_lds_dwordx4 v[206:207], off
	v_lshl_add_u64 v[196:197], s[84:85], 0, v[130:131]
	s_mov_b32 m0, s83
	v_lshl_add_u64 v[208:209], s[58:59], 0, v[220:221]
	global_load_lds_dwordx4 v[196:197], off
	v_lshl_add_u64 v[196:197], s[84:85], 0, v[216:217]
	s_add_i32 m0, s83, 0x2000
	v_lshl_add_u64 v[210:211], s[58:59], 0, v[218:219]
	global_load_lds_dwordx4 v[196:197], off
	s_mov_b32 m0, s67
	s_nop 0
	global_load_lds_dwordx4 v[208:209], off
	s_mov_b32 m0, s68
	s_nop 0
	global_load_lds_dwordx4 v[210:211], off
	s_waitcnt vmcnt(8)
	s_waitcnt lgkmcnt(0)
	s_barrier
	v_mfma_f32_16x16x32_bf16 v[86:89], v[62:65], v[140:143], v[86:89]
	v_mfma_f32_16x16x32_bf16 v[54:57], v[70:73], v[140:143], v[54:57]
	v_mfma_f32_16x16x32_bf16 v[46:49], v[62:65], v[156:159], v[46:49]
	v_mfma_f32_16x16x32_bf16 v[38:41], v[70:73], v[156:159], v[38:41]
	v_mfma_f32_16x16x32_bf16 v[30:33], v[62:65], v[180:183], v[30:33]
	v_mfma_f32_16x16x32_bf16 v[22:25], v[70:73], v[180:183], v[22:25]
	v_mfma_f32_16x16x32_bf16 v[14:17], v[62:65], v[188:191], v[14:17]
	v_mfma_f32_16x16x32_bf16 v[6:9], v[70:73], v[188:191], v[6:9]
	v_mfma_f32_16x16x32_bf16 v[86:89], v[66:69], v[148:151], v[86:89]
	v_mfma_f32_16x16x32_bf16 v[54:57], v[74:77], v[148:151], v[54:57]
	v_mfma_f32_16x16x32_bf16 v[46:49], v[66:69], v[164:167], v[46:49]
	v_mfma_f32_16x16x32_bf16 v[38:41], v[74:77], v[164:167], v[38:41]
	v_mfma_f32_16x16x32_bf16 v[30:33], v[66:69], v[184:187], v[30:33]
	v_mfma_f32_16x16x32_bf16 v[22:25], v[74:77], v[184:187], v[22:25]
	v_mfma_f32_16x16x32_bf16 v[14:17], v[66:69], v[192:195], v[14:17]
	v_mfma_f32_16x16x32_bf16 v[6:9], v[74:77], v[192:195], v[6:9]
	v_mfma_f32_16x16x32_bf16 v[58:61], v[78:81], v[140:143], v[58:61]
	v_mfma_f32_16x16x32_bf16 v[50:53], v[90:93], v[140:143], v[50:53]
	v_mfma_f32_16x16x32_bf16 v[42:45], v[78:81], v[156:159], v[42:45]
	v_mfma_f32_16x16x32_bf16 v[34:37], v[90:93], v[156:159], v[34:37]
	v_mfma_f32_16x16x32_bf16 v[26:29], v[78:81], v[180:183], v[26:29]
	v_mfma_f32_16x16x32_bf16 v[18:21], v[90:93], v[180:183], v[18:21]
	v_mfma_f32_16x16x32_bf16 v[10:13], v[78:81], v[188:191], v[10:13]
	v_mfma_f32_16x16x32_bf16 v[2:5], v[90:93], v[188:191], v[2:5]
	v_mfma_f32_16x16x32_bf16 v[58:61], v[82:85], v[148:151], v[58:61]
	v_mfma_f32_16x16x32_bf16 v[50:53], v[94:97], v[148:151], v[50:53]
	v_mfma_f32_16x16x32_bf16 v[42:45], v[82:85], v[164:167], v[42:45]
	v_mfma_f32_16x16x32_bf16 v[34:37], v[94:97], v[164:167], v[34:37]
	v_mfma_f32_16x16x32_bf16 v[26:29], v[82:85], v[184:187], v[26:29]
	v_mfma_f32_16x16x32_bf16 v[18:21], v[94:97], v[184:187], v[18:21]
	v_mfma_f32_16x16x32_bf16 v[10:13], v[82:85], v[192:195], v[10:13]
	v_mfma_f32_16x16x32_bf16 v[2:5], v[94:97], v[192:195], v[2:5]
	s_barrier
	s_add_i32 s83, 0, 0x18000
	s_add_i32 s84, 0, 0x1c000
	v_add_u32_e32 v74, s83, v244
	v_add_u32_e32 v94, s84, v244
	ds_read_b128 v[62:65], v74
	ds_read_b128 v[66:69], v74 offset:1024
	ds_read_b128 v[70:73], v74 offset:2048
	ds_read_b128 v[74:77], v74 offset:3072
	ds_read_b128 v[78:81], v94
	ds_read_b128 v[82:85], v94 offset:1024
	ds_read_b128 v[90:93], v94 offset:2048
	ds_read_b128 v[94:97], v94 offset:3072
	s_add_u32 s58, s58, 0x100000
	s_addc_u32 s59, s59, 0
	s_mov_b32 m0, s69
	v_lshl_add_u64 v[156:157], s[58:59], 0, v[220:221]
	ds_read_b128 v[140:143], v250 offset:32768
	ds_read_b128 v[148:151], v250 offset:33792
	ds_read_b128 v[180:183], v250 offset:34816
	ds_read_b128 v[184:187], v250 offset:35840
	ds_read_b128 v[188:191], v250 offset:36864
	ds_read_b128 v[192:195], v250 offset:37888
	ds_read_b128 v[196:199], v250 offset:38912
	ds_read_b128 v[200:203], v250 offset:39936
	global_load_lds_dwordx4 v[156:157], off
	v_lshl_add_u64 v[156:157], s[58:59], 0, v[218:219]
	s_mov_b32 m0, s70
	s_nop 0
	global_load_lds_dwordx4 v[156:157], off
	s_waitcnt vmcnt(8)
	s_waitcnt lgkmcnt(0)
	s_barrier
	v_mfma_f32_16x16x32_bf16 v[156:159], v[62:65], v[140:143], v[176:179]
	v_mfma_f32_16x16x32_bf16 v[176:179], v[66:69], v[148:151], v[156:159]
	v_mfma_f32_16x16x32_bf16 v[156:159], v[70:73], v[140:143], v[168:171]
	v_mfma_f32_16x16x32_bf16 v[168:171], v[74:77], v[148:151], v[156:159]
	v_mfma_f32_16x16x32_bf16 v[156:159], v[62:65], v[180:183], v[160:163]
	v_mfma_f32_16x16x32_bf16 v[152:155], v[70:73], v[180:183], v[152:155]
	v_mfma_f32_16x16x32_bf16 v[144:147], v[62:65], v[188:191], v[144:147]
	v_mfma_f32_16x16x32_bf16 v[136:139], v[70:73], v[188:191], v[136:139]
	v_mfma_f32_16x16x32_bf16 v[126:129], v[62:65], v[196:199], v[126:129]
	v_mfma_f32_16x16x32_bf16 v[118:121], v[70:73], v[196:199], v[118:121]
	v_mfma_f32_16x16x32_bf16 v[160:163], v[66:69], v[184:187], v[156:159]
	v_mfma_f32_16x16x32_bf16 v[152:155], v[74:77], v[184:187], v[152:155]
	v_mfma_f32_16x16x32_bf16 v[144:147], v[66:69], v[192:195], v[144:147]
	v_mfma_f32_16x16x32_bf16 v[136:139], v[74:77], v[192:195], v[136:139]
	v_mfma_f32_16x16x32_bf16 v[126:129], v[66:69], v[200:203], v[126:129]
	v_mfma_f32_16x16x32_bf16 v[118:121], v[74:77], v[200:203], v[118:121]
	v_mfma_f32_16x16x32_bf16 v[98:101], v[90:93], v[140:143], v[98:101]
	v_mfma_f32_16x16x32_bf16 v[156:159], v[78:81], v[140:143], v[172:175]
	v_mfma_f32_16x16x32_bf16 v[164:167], v[94:97], v[148:151], v[98:101]
	v_mfma_f32_16x16x32_bf16 v[98:101], v[78:81], v[180:183], v[102:105]
	v_mfma_f32_16x16x32_bf16 v[172:175], v[82:85], v[148:151], v[156:159]
	v_mfma_f32_16x16x32_bf16 v[156:159], v[82:85], v[184:187], v[98:101]
	v_mfma_f32_16x16x32_bf16 v[98:101], v[90:93], v[180:183], v[106:109]
	v_mfma_f32_16x16x32_bf16 v[148:151], v[94:97], v[184:187], v[98:101]
	v_mfma_f32_16x16x32_bf16 v[98:101], v[78:81], v[188:191], v[110:113]
	v_mfma_f32_16x16x32_bf16 v[140:143], v[82:85], v[192:195], v[98:101]
	v_mfma_f32_16x16x32_bf16 v[98:101], v[90:93], v[188:191], v[132:135]
	v_mfma_f32_16x16x32_bf16 v[132:135], v[94:97], v[192:195], v[98:101]
	v_mfma_f32_16x16x32_bf16 v[98:101], v[78:81], v[196:199], v[122:125]
	v_mfma_f32_16x16x32_bf16 v[122:125], v[82:85], v[200:203], v[98:101]
	v_mfma_f32_16x16x32_bf16 v[98:101], v[90:93], v[196:199], v[114:117]
	v_mfma_f32_16x16x32_bf16 v[114:117], v[94:97], v[200:203], v[98:101]
	s_barrier
	s_add_i32 s58, s83, s66
	v_lshl_add_u64 v[196:197], v[204:205], 0, s[18:19]
	s_mov_b32 m0, s58
	s_nop 1
	ds_read_b128 v[98:101], v250 offset:49152
	ds_read_b128 v[102:105], v250 offset:50176
	ds_read_b128 v[106:109], v250 offset:51200
	ds_read_b128 v[110:113], v250 offset:52224
	ds_read_b128 v[180:183], v250 offset:53248
	ds_read_b128 v[184:187], v250 offset:54272
	ds_read_b128 v[188:191], v250 offset:55296
	ds_read_b128 v[192:195], v250 offset:56320
	global_load_lds_dwordx4 v[196:197], off
	s_add_i32 m0, s58, 0x2000
	s_add_u32 s46, s46, 0x100080
	v_lshl_add_u64 v[196:197], v[206:207], 0, s[18:19]
	s_addc_u32 s47, s47, 0
	s_add_i32 s58, s84, s66
	global_load_lds_dwordx4 v[196:197], off
	v_lshl_add_u64 v[196:197], s[46:47], 0, v[130:131]
	s_mov_b32 m0, s58
	s_nop 0
	global_load_lds_dwordx4 v[196:197], off
	v_lshl_add_u64 v[196:197], s[46:47], 0, v[216:217]
	s_add_i32 m0, s58, 0x2000
	s_nop 0
	global_load_lds_dwordx4 v[196:197], off
	v_lshl_add_u64 v[196:197], v[208:209], 0, s[18:19]
	s_mov_b32 m0, s74
	s_nop 0
	global_load_lds_dwordx4 v[196:197], off
	v_lshl_add_u64 v[196:197], v[210:211], 0, s[18:19]
	s_mov_b32 m0, s75
	s_nop 0
	global_load_lds_dwordx4 v[196:197], off
	s_waitcnt vmcnt(8)
	s_waitcnt lgkmcnt(0)
	s_barrier
	v_mfma_f32_16x16x32_bf16 v[86:89], v[62:65], v[98:101], v[86:89]
	v_mfma_f32_16x16x32_bf16 v[54:57], v[70:73], v[98:101], v[54:57]
	v_mfma_f32_16x16x32_bf16 v[46:49], v[62:65], v[106:109], v[46:49]
	v_mfma_f32_16x16x32_bf16 v[38:41], v[70:73], v[106:109], v[38:41]
	v_mfma_f32_16x16x32_bf16 v[30:33], v[62:65], v[180:183], v[30:33]
	v_mfma_f32_16x16x32_bf16 v[22:25], v[70:73], v[180:183], v[22:25]
	v_mfma_f32_16x16x32_bf16 v[14:17], v[62:65], v[188:191], v[14:17]
	v_mfma_f32_16x16x32_bf16 v[6:9], v[70:73], v[188:191], v[6:9]
	v_mfma_f32_16x16x32_bf16 v[86:89], v[66:69], v[102:105], v[86:89]
	v_mfma_f32_16x16x32_bf16 v[54:57], v[74:77], v[102:105], v[54:57]
	v_mfma_f32_16x16x32_bf16 v[46:49], v[66:69], v[110:113], v[46:49]
	v_mfma_f32_16x16x32_bf16 v[38:41], v[74:77], v[110:113], v[38:41]
	v_mfma_f32_16x16x32_bf16 v[30:33], v[66:69], v[184:187], v[30:33]
	v_mfma_f32_16x16x32_bf16 v[22:25], v[74:77], v[184:187], v[22:25]
	v_mfma_f32_16x16x32_bf16 v[14:17], v[66:69], v[192:195], v[14:17]
	v_mfma_f32_16x16x32_bf16 v[6:9], v[74:77], v[192:195], v[6:9]
	v_mfma_f32_16x16x32_bf16 v[58:61], v[78:81], v[98:101], v[58:61]
	v_mfma_f32_16x16x32_bf16 v[50:53], v[90:93], v[98:101], v[50:53]
	v_mfma_f32_16x16x32_bf16 v[42:45], v[78:81], v[106:109], v[42:45]
	v_mfma_f32_16x16x32_bf16 v[34:37], v[90:93], v[106:109], v[34:37]
	v_mfma_f32_16x16x32_bf16 v[26:29], v[78:81], v[180:183], v[26:29]
	v_mfma_f32_16x16x32_bf16 v[18:21], v[90:93], v[180:183], v[18:21]
	v_mfma_f32_16x16x32_bf16 v[10:13], v[78:81], v[188:191], v[10:13]
	v_mfma_f32_16x16x32_bf16 v[2:5], v[90:93], v[188:191], v[2:5]
	v_mfma_f32_16x16x32_bf16 v[58:61], v[82:85], v[102:105], v[58:61]
	v_mfma_f32_16x16x32_bf16 v[50:53], v[94:97], v[102:105], v[50:53]
	v_mfma_f32_16x16x32_bf16 v[42:45], v[82:85], v[110:113], v[42:45]
	v_mfma_f32_16x16x32_bf16 v[34:37], v[94:97], v[110:113], v[34:37]
	v_mfma_f32_16x16x32_bf16 v[26:29], v[82:85], v[184:187], v[26:29]
	v_mfma_f32_16x16x32_bf16 v[18:21], v[94:97], v[184:187], v[18:21]
	v_mfma_f32_16x16x32_bf16 v[10:13], v[82:85], v[192:195], v[10:13]
	v_mfma_f32_16x16x32_bf16 v[2:5], v[94:97], v[192:195], v[2:5]
	s_barrier
	s_add_i32 s82, s82, 2
	s_add_u32 s2, s2, 0x100
	s_addc_u32 s3, s3, 0
	s_add_u32 s80, s80, 0x100
	s_addc_u32 s81, s81, 0
	s_cmp_gt_u32 s82, 61
	s_cbranch_scc0 .LBB0_1024
	v_mov_b64_e32 v[214:215], 0x400
	s_and_b64 vcc, exec, s[16:17]
	s_cbranch_vccz .LBB0_1027
	s_barrier

.LBB0_1328:
	s_add_u32 s24, s22, 0x100
	s_addc_u32 s25, s23, 0
	s_add_i32 s57, 0, 0x10000
	s_cmpk_eq_i32 s56, 0xa8
	s_cselect_b32 s29, s3, s25
	s_cselect_b32 s28, s2, s24
	v_add_u32_e32 v146, s57, v149
	s_cselect_b32 s27, s17, s55
	s_cselect_b32 s26, s16, s54
	s_add_i32 s58, 0, 0x14000
	ds_read_b128 v[142:145], v146
	ds_read_b128 v[152:155], v146 offset:1024
	ds_read_b128 v[156:159], v146 offset:2048
	ds_read_b128 v[160:163], v146 offset:3072
	v_add_u32_e32 v146, s58, v149
	ds_read_b128 v[164:167], v146
	ds_read_b128 v[168:171], v146 offset:1024
	ds_read_b128 v[172:175], v146 offset:2048
	ds_read_b128 v[176:179], v146 offset:3072
	v_lshl_add_u64 v[146:147], s[22:23], 0, v[138:139]
	s_add_i32 m0, s41, 0xc000
	ds_read_b128 v[180:183], v151
	ds_read_b128 v[184:187], v151 offset:1024
	ds_read_b128 v[188:191], v151 offset:2048
	ds_read_b128 v[192:195], v151 offset:3072
	ds_read_b128 v[196:199], v151 offset:4096
	ds_read_b128 v[200:203], v151 offset:5120
	ds_read_b128 v[204:207], v151 offset:6144
	ds_read_b128 v[208:211], v151 offset:7168
	global_load_lds_dwordx4 v[146:147], off
	v_lshl_add_u64 v[146:147], s[22:23], 0, v[140:141]
	s_add_i32 m0, s41, 0xe000
	s_nop 0
	global_load_lds_dwordx4 v[146:147], off
	s_waitcnt vmcnt(8)
	s_waitcnt lgkmcnt(0)
	s_barrier
	v_mfma_f32_16x16x32_bf16 v[126:129], v[142:145], v[180:183], v[126:129]
	v_mfma_f32_16x16x32_bf16 v[122:125], v[156:159], v[180:183], v[122:125]
	v_mfma_f32_16x16x32_bf16 v[110:113], v[142:145], v[188:191], v[110:113]
	v_mfma_f32_16x16x32_bf16 v[106:109], v[156:159], v[188:191], v[106:109]
	v_mfma_f32_16x16x32_bf16 v[94:97], v[142:145], v[196:199], v[94:97]
	v_mfma_f32_16x16x32_bf16 v[90:93], v[156:159], v[196:199], v[90:93]
	v_mfma_f32_16x16x32_bf16 v[78:81], v[142:145], v[204:207], v[78:81]
	v_mfma_f32_16x16x32_bf16 v[74:77], v[156:159], v[204:207], v[74:77]
	v_mfma_f32_16x16x32_bf16 v[126:129], v[152:155], v[184:187], v[126:129]
	v_mfma_f32_16x16x32_bf16 v[122:125], v[160:163], v[184:187], v[122:125]
	v_mfma_f32_16x16x32_bf16 v[110:113], v[152:155], v[192:195], v[110:113]
	v_mfma_f32_16x16x32_bf16 v[106:109], v[160:163], v[192:195], v[106:109]
	v_mfma_f32_16x16x32_bf16 v[94:97], v[152:155], v[200:203], v[94:97]
	v_mfma_f32_16x16x32_bf16 v[90:93], v[160:163], v[200:203], v[90:93]
	v_mfma_f32_16x16x32_bf16 v[78:81], v[152:155], v[208:211], v[78:81]
	v_mfma_f32_16x16x32_bf16 v[74:77], v[160:163], v[208:211], v[74:77]
	v_mfma_f32_16x16x32_bf16 v[118:121], v[164:167], v[180:183], v[118:121]
	v_mfma_f32_16x16x32_bf16 v[114:117], v[172:175], v[180:183], v[114:117]
	v_mfma_f32_16x16x32_bf16 v[102:105], v[164:167], v[188:191], v[102:105]
	v_mfma_f32_16x16x32_bf16 v[98:101], v[172:175], v[188:191], v[98:101]
	v_mfma_f32_16x16x32_bf16 v[86:89], v[164:167], v[196:199], v[86:89]
	v_mfma_f32_16x16x32_bf16 v[82:85], v[172:175], v[196:199], v[82:85]
	v_mfma_f32_16x16x32_bf16 v[70:73], v[164:167], v[204:207], v[70:73]
	v_mfma_f32_16x16x32_bf16 v[66:69], v[172:175], v[204:207], v[66:69]
	v_mfma_f32_16x16x32_bf16 v[118:121], v[168:171], v[184:187], v[118:121]
	v_mfma_f32_16x16x32_bf16 v[114:117], v[176:179], v[184:187], v[114:117]
	v_mfma_f32_16x16x32_bf16 v[102:105], v[168:171], v[192:195], v[102:105]
	v_mfma_f32_16x16x32_bf16 v[98:101], v[176:179], v[192:195], v[98:101]
	v_mfma_f32_16x16x32_bf16 v[86:89], v[168:171], v[200:203], v[86:89]
	v_mfma_f32_16x16x32_bf16 v[82:85], v[176:179], v[200:203], v[82:85]
	v_mfma_f32_16x16x32_bf16 v[70:73], v[168:171], v[208:211], v[70:73]
	v_mfma_f32_16x16x32_bf16 v[66:69], v[176:179], v[208:211], v[66:69]
	s_barrier
	s_add_i32 s22, s57, s40
	v_lshl_add_u64 v[146:147], s[26:27], 0, v[130:131]
	s_mov_b32 m0, s22
	ds_read_b128 v[180:183], v151 offset:16384
	ds_read_b128 v[184:187], v151 offset:17408
	ds_read_b128 v[188:191], v151 offset:18432
	ds_read_b128 v[192:195], v151 offset:19456
	ds_read_b128 v[196:199], v151 offset:20480
	ds_read_b128 v[200:203], v151 offset:21504
	ds_read_b128 v[204:207], v151 offset:22528
	ds_read_b128 v[208:211], v151 offset:23552
	global_load_lds_dwordx4 v[146:147], off
	s_add_i32 m0, s22, 0x2000
	s_add_u32 s22, s26, 0x2b0000
	v_lshl_add_u64 v[212:213], s[26:27], 0, v[132:133]
	s_addc_u32 s23, s27, 0
	s_add_i32 s57, s58, s40
	global_load_lds_dwordx4 v[212:213], off
	v_lshl_add_u64 v[216:217], s[22:23], 0, v[130:131]
	s_mov_b32 m0, s57
	v_lshl_add_u64 v[218:219], s[28:29], 0, v[134:135]
	global_load_lds_dwordx4 v[216:217], off
	v_lshl_add_u64 v[216:217], s[22:23], 0, v[132:133]
	s_add_i32 m0, s57, 0x2000
	s_nop 0
	global_load_lds_dwordx4 v[216:217], off
	v_lshl_add_u64 v[216:217], s[28:29], 0, v[136:137]
	s_mov_b32 m0, s41
	s_nop 0
	global_load_lds_dwordx4 v[216:217], off
	s_mov_b32 m0, s44
	s_nop 0
	global_load_lds_dwordx4 v[218:219], off
	s_waitcnt vmcnt(8)
	s_waitcnt lgkmcnt(0)
	s_barrier
	v_mfma_f32_16x16x32_bf16 v[62:65], v[142:145], v[180:183], v[62:65]
	v_mfma_f32_16x16x32_bf16 v[58:61], v[156:159], v[180:183], v[58:61]
	v_mfma_f32_16x16x32_bf16 v[46:49], v[142:145], v[188:191], v[46:49]
	v_mfma_f32_16x16x32_bf16 v[42:45], v[156:159], v[188:191], v[42:45]
	v_mfma_f32_16x16x32_bf16 v[30:33], v[142:145], v[196:199], v[30:33]
	v_mfma_f32_16x16x32_bf16 v[26:29], v[156:159], v[196:199], v[26:29]
	v_mfma_f32_16x16x32_bf16 v[14:17], v[142:145], v[204:207], v[14:17]
	v_mfma_f32_16x16x32_bf16 v[10:13], v[156:159], v[204:207], v[10:13]
	v_mfma_f32_16x16x32_bf16 v[62:65], v[152:155], v[184:187], v[62:65]
	v_mfma_f32_16x16x32_bf16 v[58:61], v[160:163], v[184:187], v[58:61]
	v_mfma_f32_16x16x32_bf16 v[46:49], v[152:155], v[192:195], v[46:49]
	v_mfma_f32_16x16x32_bf16 v[42:45], v[160:163], v[192:195], v[42:45]
	v_mfma_f32_16x16x32_bf16 v[30:33], v[152:155], v[200:203], v[30:33]
	v_mfma_f32_16x16x32_bf16 v[26:29], v[160:163], v[200:203], v[26:29]
	v_mfma_f32_16x16x32_bf16 v[14:17], v[152:155], v[208:211], v[14:17]
	v_mfma_f32_16x16x32_bf16 v[10:13], v[160:163], v[208:211], v[10:13]
	v_mfma_f32_16x16x32_bf16 v[54:57], v[164:167], v[180:183], v[54:57]
	v_mfma_f32_16x16x32_bf16 v[50:53], v[172:175], v[180:183], v[50:53]
	v_mfma_f32_16x16x32_bf16 v[38:41], v[164:167], v[188:191], v[38:41]
	v_mfma_f32_16x16x32_bf16 v[34:37], v[172:175], v[188:191], v[34:37]
	v_mfma_f32_16x16x32_bf16 v[22:25], v[164:167], v[196:199], v[22:25]
	v_mfma_f32_16x16x32_bf16 v[18:21], v[172:175], v[196:199], v[18:21]
	v_mfma_f32_16x16x32_bf16 v[6:9], v[164:167], v[204:207], v[6:9]
	v_mfma_f32_16x16x32_bf16 v[2:5], v[172:175], v[204:207], v[2:5]
	v_mfma_f32_16x16x32_bf16 v[54:57], v[168:171], v[184:187], v[54:57]
	v_mfma_f32_16x16x32_bf16 v[50:53], v[176:179], v[184:187], v[50:53]
	v_mfma_f32_16x16x32_bf16 v[38:41], v[168:171], v[192:195], v[38:41]
	v_mfma_f32_16x16x32_bf16 v[34:37], v[176:179], v[192:195], v[34:37]
	v_mfma_f32_16x16x32_bf16 v[22:25], v[168:171], v[200:203], v[22:25]
	v_mfma_f32_16x16x32_bf16 v[18:21], v[176:179], v[200:203], v[18:21]
	v_mfma_f32_16x16x32_bf16 v[6:9], v[168:171], v[208:211], v[6:9]
	v_mfma_f32_16x16x32_bf16 v[2:5], v[176:179], v[208:211], v[2:5]
	s_barrier
	s_add_i32 s57, 0, 0x18000
	s_add_i32 s58, 0, 0x1c000
	v_add_u32_e32 v160, s57, v149
	v_add_u32_e32 v176, s58, v149
	ds_read_b128 v[142:145], v160
	ds_read_b128 v[152:155], v160 offset:1024
	ds_read_b128 v[156:159], v160 offset:2048
	ds_read_b128 v[160:163], v160 offset:3072
	ds_read_b128 v[164:167], v176
	ds_read_b128 v[168:171], v176 offset:1024
	ds_read_b128 v[172:175], v176 offset:2048
	ds_read_b128 v[176:179], v176 offset:3072
	s_add_u32 s22, s28, 0x2b0000
	s_addc_u32 s23, s29, 0
	s_mov_b32 m0, s45
	v_lshl_add_u64 v[220:221], s[22:23], 0, v[136:137]
	ds_read_b128 v[180:183], v151 offset:32768
	ds_read_b128 v[184:187], v151 offset:33792
	ds_read_b128 v[188:191], v151 offset:34816
	ds_read_b128 v[192:195], v151 offset:35840
	ds_read_b128 v[196:199], v151 offset:36864
	ds_read_b128 v[200:203], v151 offset:37888
	ds_read_b128 v[204:207], v151 offset:38912
	ds_read_b128 v[208:211], v151 offset:39936
	global_load_lds_dwordx4 v[220:221], off
	v_lshl_add_u64 v[220:221], s[22:23], 0, v[134:135]
	s_mov_b32 m0, s46
	s_nop 0
	global_load_lds_dwordx4 v[220:221], off
	s_waitcnt vmcnt(8)
	s_waitcnt lgkmcnt(0)
	s_barrier
	v_mfma_f32_16x16x32_bf16 v[126:129], v[142:145], v[180:183], v[126:129]
	v_mfma_f32_16x16x32_bf16 v[122:125], v[156:159], v[180:183], v[122:125]
	v_mfma_f32_16x16x32_bf16 v[110:113], v[142:145], v[188:191], v[110:113]
	v_mfma_f32_16x16x32_bf16 v[106:109], v[156:159], v[188:191], v[106:109]
	v_mfma_f32_16x16x32_bf16 v[94:97], v[142:145], v[196:199], v[94:97]
	v_mfma_f32_16x16x32_bf16 v[90:93], v[156:159], v[196:199], v[90:93]
	v_mfma_f32_16x16x32_bf16 v[78:81], v[142:145], v[204:207], v[78:81]
	v_mfma_f32_16x16x32_bf16 v[74:77], v[156:159], v[204:207], v[74:77]
	v_mfma_f32_16x16x32_bf16 v[126:129], v[152:155], v[184:187], v[126:129]
	v_mfma_f32_16x16x32_bf16 v[122:125], v[160:163], v[184:187], v[122:125]
	v_mfma_f32_16x16x32_bf16 v[110:113], v[152:155], v[192:195], v[110:113]
	v_mfma_f32_16x16x32_bf16 v[106:109], v[160:163], v[192:195], v[106:109]
	v_mfma_f32_16x16x32_bf16 v[94:97], v[152:155], v[200:203], v[94:97]
	v_mfma_f32_16x16x32_bf16 v[90:93], v[160:163], v[200:203], v[90:93]
	v_mfma_f32_16x16x32_bf16 v[78:81], v[152:155], v[208:211], v[78:81]
	v_mfma_f32_16x16x32_bf16 v[74:77], v[160:163], v[208:211], v[74:77]
	v_mfma_f32_16x16x32_bf16 v[118:121], v[164:167], v[180:183], v[118:121]
	v_mfma_f32_16x16x32_bf16 v[114:117], v[172:175], v[180:183], v[114:117]
	v_mfma_f32_16x16x32_bf16 v[102:105], v[164:167], v[188:191], v[102:105]
	v_mfma_f32_16x16x32_bf16 v[98:101], v[172:175], v[188:191], v[98:101]
	v_mfma_f32_16x16x32_bf16 v[86:89], v[164:167], v[196:199], v[86:89]
	v_mfma_f32_16x16x32_bf16 v[82:85], v[172:175], v[196:199], v[82:85]
	v_mfma_f32_16x16x32_bf16 v[70:73], v[164:167], v[204:207], v[70:73]
	v_mfma_f32_16x16x32_bf16 v[66:69], v[172:175], v[204:207], v[66:69]
	v_mfma_f32_16x16x32_bf16 v[118:121], v[168:171], v[184:187], v[118:121]
	v_mfma_f32_16x16x32_bf16 v[114:117], v[176:179], v[184:187], v[114:117]
	v_mfma_f32_16x16x32_bf16 v[102:105], v[168:171], v[192:195], v[102:105]
	v_mfma_f32_16x16x32_bf16 v[98:101], v[176:179], v[192:195], v[98:101]
	v_mfma_f32_16x16x32_bf16 v[86:89], v[168:171], v[200:203], v[86:89]
	v_mfma_f32_16x16x32_bf16 v[82:85], v[176:179], v[200:203], v[82:85]
	v_mfma_f32_16x16x32_bf16 v[70:73], v[168:171], v[208:211], v[70:73]
	v_mfma_f32_16x16x32_bf16 v[66:69], v[176:179], v[208:211], v[66:69]
	s_barrier
	s_add_i32 s22, s57, s40
	v_lshl_add_u64 v[146:147], v[146:147], 0, s[18:19]
	s_mov_b32 m0, s22
	ds_read_b128 v[180:183], v151 offset:49152
	ds_read_b128 v[184:187], v151 offset:50176
	ds_read_b128 v[188:191], v151 offset:51200
	ds_read_b128 v[192:195], v151 offset:52224
	ds_read_b128 v[196:199], v151 offset:53248
	ds_read_b128 v[200:203], v151 offset:54272
	ds_read_b128 v[204:207], v151 offset:55296
	ds_read_b128 v[208:211], v151 offset:56320
	global_load_lds_dwordx4 v[146:147], off
	s_add_i32 m0, s22, 0x2000
	s_add_u32 s22, s26, 0x2b0080
	v_lshl_add_u64 v[146:147], v[212:213], 0, s[18:19]
	s_addc_u32 s23, s27, 0
	s_add_i32 s26, s58, s40
	global_load_lds_dwordx4 v[146:147], off
	v_lshl_add_u64 v[146:147], s[22:23], 0, v[130:131]
	s_mov_b32 m0, s26
	s_nop 0
	global_load_lds_dwordx4 v[146:147], off
	v_lshl_add_u64 v[146:147], s[22:23], 0, v[132:133]
	s_add_i32 m0, s26, 0x2000
	s_nop 0
	global_load_lds_dwordx4 v[146:147], off
	v_lshl_add_u64 v[146:147], v[216:217], 0, s[18:19]
	s_mov_b32 m0, s47
	s_nop 0
	global_load_lds_dwordx4 v[146:147], off
	v_lshl_add_u64 v[146:147], v[218:219], 0, s[18:19]
	s_mov_b32 m0, s48
	s_nop 0
	global_load_lds_dwordx4 v[146:147], off
	s_waitcnt vmcnt(8)
	s_waitcnt lgkmcnt(0)
	s_barrier
	v_mfma_f32_16x16x32_bf16 v[62:65], v[142:145], v[180:183], v[62:65]
	v_mfma_f32_16x16x32_bf16 v[58:61], v[156:159], v[180:183], v[58:61]
	v_mfma_f32_16x16x32_bf16 v[46:49], v[142:145], v[188:191], v[46:49]
	v_mfma_f32_16x16x32_bf16 v[42:45], v[156:159], v[188:191], v[42:45]
	v_mfma_f32_16x16x32_bf16 v[30:33], v[142:145], v[196:199], v[30:33]
	v_mfma_f32_16x16x32_bf16 v[26:29], v[156:159], v[196:199], v[26:29]
	v_mfma_f32_16x16x32_bf16 v[14:17], v[142:145], v[204:207], v[14:17]
	v_mfma_f32_16x16x32_bf16 v[10:13], v[156:159], v[204:207], v[10:13]
	v_mfma_f32_16x16x32_bf16 v[62:65], v[152:155], v[184:187], v[62:65]
	v_mfma_f32_16x16x32_bf16 v[58:61], v[160:163], v[184:187], v[58:61]
	v_mfma_f32_16x16x32_bf16 v[46:49], v[152:155], v[192:195], v[46:49]
	v_mfma_f32_16x16x32_bf16 v[42:45], v[160:163], v[192:195], v[42:45]
	v_mfma_f32_16x16x32_bf16 v[30:33], v[152:155], v[200:203], v[30:33]
	v_mfma_f32_16x16x32_bf16 v[26:29], v[160:163], v[200:203], v[26:29]
	v_mfma_f32_16x16x32_bf16 v[14:17], v[152:155], v[208:211], v[14:17]
	v_mfma_f32_16x16x32_bf16 v[10:13], v[160:163], v[208:211], v[10:13]
	v_mfma_f32_16x16x32_bf16 v[54:57], v[164:167], v[180:183], v[54:57]
	v_mfma_f32_16x16x32_bf16 v[50:53], v[172:175], v[180:183], v[50:53]
	v_mfma_f32_16x16x32_bf16 v[38:41], v[164:167], v[188:191], v[38:41]
	v_mfma_f32_16x16x32_bf16 v[34:37], v[172:175], v[188:191], v[34:37]
	v_mfma_f32_16x16x32_bf16 v[22:25], v[164:167], v[196:199], v[22:25]
	v_mfma_f32_16x16x32_bf16 v[18:21], v[172:175], v[196:199], v[18:21]
	v_mfma_f32_16x16x32_bf16 v[6:9], v[164:167], v[204:207], v[6:9]
	v_mfma_f32_16x16x32_bf16 v[2:5], v[172:175], v[204:207], v[2:5]
	v_mfma_f32_16x16x32_bf16 v[54:57], v[168:171], v[184:187], v[54:57]
	v_mfma_f32_16x16x32_bf16 v[50:53], v[176:179], v[184:187], v[50:53]
	v_mfma_f32_16x16x32_bf16 v[38:41], v[168:171], v[192:195], v[38:41]
	v_mfma_f32_16x16x32_bf16 v[34:37], v[176:179], v[192:195], v[34:37]
	v_mfma_f32_16x16x32_bf16 v[22:25], v[168:171], v[200:203], v[22:25]
	v_mfma_f32_16x16x32_bf16 v[18:21], v[176:179], v[200:203], v[18:21]
	v_mfma_f32_16x16x32_bf16 v[6:9], v[168:171], v[208:211], v[6:9]
	v_mfma_f32_16x16x32_bf16 v[2:5], v[176:179], v[208:211], v[2:5]
	s_barrier
	s_add_i32 s56, s56, 2
	s_add_u32 s54, s54, 0x100
	s_addc_u32 s55, s55, 0
	s_cmpk_gt_u32 s56, 0xa9
	s_mov_b64 s[22:23], s[24:25]
	s_cbranch_scc0 .LBB0_1328
	s_and_b64 vcc, exec, s[12:13]
	s_cbranch_vccz .LBB0_1331
	s_barrier

.LBB0_1354:
	s_add_u32 s24, s22, 0x100
	s_addc_u32 s25, s23, 0
	s_add_i32 s60, 0, 0x10000
	s_cmpk_eq_i32 s59, 0xa8
	s_cselect_b32 s29, s3, s25
	s_cselect_b32 s28, s2, s24
	v_add_u32_e32 v149, s60, v194
	s_cselect_b32 s27, s13, s58
	s_cselect_b32 s26, s12, s57
	s_add_i32 s61, 0, 0x14000
	ds_read_b128 v[132:135], v149
	ds_read_b128 v[150:153], v149 offset:1024
	ds_read_b128 v[154:157], v149 offset:2048
	ds_read_b128 v[158:161], v149 offset:3072
	v_add_u32_e32 v149, s61, v194
	ds_read_b128 v[162:165], v149
	ds_read_b128 v[166:169], v149 offset:1024
	ds_read_b128 v[170:173], v149 offset:2048
	ds_read_b128 v[174:177], v149 offset:3072
	v_lshl_add_u64 v[190:191], s[22:23], 0, v[144:145]
	s_add_i32 m0, s48, 0xc000
	ds_read_b128 v[178:181], v196
	ds_read_b128 v[182:185], v196 offset:1024
	ds_read_b128 v[186:189], v196 offset:2048
	ds_read_b128 v[198:201], v196 offset:3072
	ds_read_b128 v[202:205], v196 offset:4096
	ds_read_b128 v[206:209], v196 offset:5120
	ds_read_b128 v[210:213], v196 offset:6144
	ds_read_b128 v[216:219], v196 offset:7168
	global_load_lds_dwordx4 v[190:191], off
	v_lshl_add_u64 v[190:191], s[22:23], 0, v[146:147]
	s_add_i32 m0, s48, 0xe000
	s_nop 0
	global_load_lds_dwordx4 v[190:191], off
	s_waitcnt vmcnt(8)
	s_waitcnt lgkmcnt(0)
	s_barrier
	v_mfma_f32_16x16x32_bf16 v[126:129], v[132:135], v[178:181], v[126:129]
	v_mfma_f32_16x16x32_bf16 v[122:125], v[154:157], v[178:181], v[122:125]
	v_mfma_f32_16x16x32_bf16 v[110:113], v[132:135], v[186:189], v[110:113]
	v_mfma_f32_16x16x32_bf16 v[106:109], v[154:157], v[186:189], v[106:109]
	v_mfma_f32_16x16x32_bf16 v[94:97], v[132:135], v[202:205], v[94:97]
	v_mfma_f32_16x16x32_bf16 v[90:93], v[154:157], v[202:205], v[90:93]
	v_mfma_f32_16x16x32_bf16 v[78:81], v[132:135], v[210:213], v[78:81]
	v_mfma_f32_16x16x32_bf16 v[74:77], v[154:157], v[210:213], v[74:77]
	v_mfma_f32_16x16x32_bf16 v[126:129], v[150:153], v[182:185], v[126:129]
	v_mfma_f32_16x16x32_bf16 v[122:125], v[158:161], v[182:185], v[122:125]
	v_mfma_f32_16x16x32_bf16 v[110:113], v[150:153], v[198:201], v[110:113]
	v_mfma_f32_16x16x32_bf16 v[106:109], v[158:161], v[198:201], v[106:109]
	v_mfma_f32_16x16x32_bf16 v[94:97], v[150:153], v[206:209], v[94:97]
	v_mfma_f32_16x16x32_bf16 v[90:93], v[158:161], v[206:209], v[90:93]
	v_mfma_f32_16x16x32_bf16 v[78:81], v[150:153], v[216:219], v[78:81]
	v_mfma_f32_16x16x32_bf16 v[74:77], v[158:161], v[216:219], v[74:77]
	v_mfma_f32_16x16x32_bf16 v[118:121], v[162:165], v[178:181], v[118:121]
	v_mfma_f32_16x16x32_bf16 v[114:117], v[170:173], v[178:181], v[114:117]
	v_mfma_f32_16x16x32_bf16 v[102:105], v[162:165], v[186:189], v[102:105]
	v_mfma_f32_16x16x32_bf16 v[98:101], v[170:173], v[186:189], v[98:101]
	v_mfma_f32_16x16x32_bf16 v[86:89], v[162:165], v[202:205], v[86:89]
	v_mfma_f32_16x16x32_bf16 v[82:85], v[170:173], v[202:205], v[82:85]
	v_mfma_f32_16x16x32_bf16 v[70:73], v[162:165], v[210:213], v[70:73]
	v_mfma_f32_16x16x32_bf16 v[66:69], v[170:173], v[210:213], v[66:69]
	v_mfma_f32_16x16x32_bf16 v[118:121], v[166:169], v[182:185], v[118:121]
	v_mfma_f32_16x16x32_bf16 v[114:117], v[174:177], v[182:185], v[114:117]
	v_mfma_f32_16x16x32_bf16 v[102:105], v[166:169], v[198:201], v[102:105]
	v_mfma_f32_16x16x32_bf16 v[98:101], v[174:177], v[198:201], v[98:101]
	v_mfma_f32_16x16x32_bf16 v[86:89], v[166:169], v[206:209], v[86:89]
	v_mfma_f32_16x16x32_bf16 v[82:85], v[174:177], v[206:209], v[82:85]
	v_mfma_f32_16x16x32_bf16 v[70:73], v[166:169], v[216:219], v[70:73]
	v_mfma_f32_16x16x32_bf16 v[66:69], v[174:177], v[216:219], v[66:69]
	s_barrier
	s_add_i32 s22, s60, s30
	v_lshl_add_u64 v[190:191], s[26:27], 0, v[140:141]
	s_mov_b32 m0, s22
	ds_read_b128 v[178:181], v196 offset:16384
	ds_read_b128 v[182:185], v196 offset:17408
	ds_read_b128 v[186:189], v196 offset:18432
	ds_read_b128 v[198:201], v196 offset:19456
	ds_read_b128 v[202:205], v196 offset:20480
	ds_read_b128 v[206:209], v196 offset:21504
	ds_read_b128 v[210:213], v196 offset:22528
	ds_read_b128 v[216:219], v196 offset:23552
	global_load_lds_dwordx4 v[190:191], off
	s_add_i32 m0, s22, 0x2000
	s_add_u32 s22, s26, 0x2b0000
	v_lshl_add_u64 v[220:221], s[26:27], 0, v[136:137]
	s_addc_u32 s23, s27, 0
	s_add_i32 s60, s61, s30
	global_load_lds_dwordx4 v[220:221], off
	v_lshl_add_u64 v[222:223], s[22:23], 0, v[140:141]
	s_mov_b32 m0, s60
	v_lshl_add_u64 v[224:225], s[28:29], 0, v[138:139]
	global_load_lds_dwordx4 v[222:223], off
	v_lshl_add_u64 v[222:223], s[22:23], 0, v[136:137]
	s_add_i32 m0, s60, 0x2000
	s_nop 0
	global_load_lds_dwordx4 v[222:223], off
	v_lshl_add_u64 v[222:223], s[28:29], 0, v[142:143]
	s_mov_b32 m0, s48
	s_nop 0
	global_load_lds_dwordx4 v[222:223], off
	s_mov_b32 m0, s49
	s_nop 0
	global_load_lds_dwordx4 v[224:225], off
	s_waitcnt vmcnt(8)
	s_waitcnt lgkmcnt(0)
	s_barrier
	v_mfma_f32_16x16x32_bf16 v[62:65], v[132:135], v[178:181], v[62:65]
	v_mfma_f32_16x16x32_bf16 v[58:61], v[154:157], v[178:181], v[58:61]
	v_mfma_f32_16x16x32_bf16 v[46:49], v[132:135], v[186:189], v[46:49]
	v_mfma_f32_16x16x32_bf16 v[42:45], v[154:157], v[186:189], v[42:45]
	v_mfma_f32_16x16x32_bf16 v[30:33], v[132:135], v[202:205], v[30:33]
	v_mfma_f32_16x16x32_bf16 v[26:29], v[154:157], v[202:205], v[26:29]
	v_mfma_f32_16x16x32_bf16 v[14:17], v[132:135], v[210:213], v[14:17]
	v_mfma_f32_16x16x32_bf16 v[10:13], v[154:157], v[210:213], v[10:13]
	v_mfma_f32_16x16x32_bf16 v[62:65], v[150:153], v[182:185], v[62:65]
	v_mfma_f32_16x16x32_bf16 v[58:61], v[158:161], v[182:185], v[58:61]
	v_mfma_f32_16x16x32_bf16 v[46:49], v[150:153], v[198:201], v[46:49]
	v_mfma_f32_16x16x32_bf16 v[42:45], v[158:161], v[198:201], v[42:45]
	v_mfma_f32_16x16x32_bf16 v[30:33], v[150:153], v[206:209], v[30:33]
	v_mfma_f32_16x16x32_bf16 v[26:29], v[158:161], v[206:209], v[26:29]
	v_mfma_f32_16x16x32_bf16 v[14:17], v[150:153], v[216:219], v[14:17]
	v_mfma_f32_16x16x32_bf16 v[10:13], v[158:161], v[216:219], v[10:13]
	v_mfma_f32_16x16x32_bf16 v[54:57], v[162:165], v[178:181], v[54:57]
	v_mfma_f32_16x16x32_bf16 v[50:53], v[170:173], v[178:181], v[50:53]
	v_mfma_f32_16x16x32_bf16 v[38:41], v[162:165], v[186:189], v[38:41]
	v_mfma_f32_16x16x32_bf16 v[34:37], v[170:173], v[186:189], v[34:37]
	v_mfma_f32_16x16x32_bf16 v[22:25], v[162:165], v[202:205], v[22:25]
	v_mfma_f32_16x16x32_bf16 v[18:21], v[170:173], v[202:205], v[18:21]
	v_mfma_f32_16x16x32_bf16 v[6:9], v[162:165], v[210:213], v[6:9]
	v_mfma_f32_16x16x32_bf16 v[2:5], v[170:173], v[210:213], v[2:5]
	v_mfma_f32_16x16x32_bf16 v[54:57], v[166:169], v[182:185], v[54:57]
	v_mfma_f32_16x16x32_bf16 v[50:53], v[174:177], v[182:185], v[50:53]
	v_mfma_f32_16x16x32_bf16 v[38:41], v[166:169], v[198:201], v[38:41]
	v_mfma_f32_16x16x32_bf16 v[34:37], v[174:177], v[198:201], v[34:37]
	v_mfma_f32_16x16x32_bf16 v[22:25], v[166:169], v[206:209], v[22:25]
	v_mfma_f32_16x16x32_bf16 v[18:21], v[174:177], v[206:209], v[18:21]
	v_mfma_f32_16x16x32_bf16 v[6:9], v[166:169], v[216:219], v[6:9]
	v_mfma_f32_16x16x32_bf16 v[2:5], v[174:177], v[216:219], v[2:5]
	s_barrier
	s_add_i32 s60, 0, 0x18000
	v_add_u32_e32 v149, s60, v194
	s_add_i32 s61, 0, 0x1c000
	ds_read_b128 v[132:135], v149
	ds_read_b128 v[150:153], v149 offset:1024
	ds_read_b128 v[154:157], v149 offset:2048
	ds_read_b128 v[158:161], v149 offset:3072
	v_add_u32_e32 v149, s61, v194
	ds_read_b128 v[162:165], v149
	ds_read_b128 v[166:169], v149 offset:1024
	ds_read_b128 v[170:173], v149 offset:2048
	ds_read_b128 v[174:177], v149 offset:3072
	s_add_u32 s22, s28, 0x2b0000
	s_addc_u32 s23, s29, 0
	s_mov_b32 m0, s50
	v_lshl_add_u64 v[226:227], s[22:23], 0, v[142:143]
	ds_read_b128 v[178:181], v196 offset:32768
	ds_read_b128 v[182:185], v196 offset:33792
	ds_read_b128 v[186:189], v196 offset:34816
	ds_read_b128 v[198:201], v196 offset:35840
	ds_read_b128 v[202:205], v196 offset:36864
	ds_read_b128 v[206:209], v196 offset:37888
	ds_read_b128 v[210:213], v196 offset:38912
	ds_read_b128 v[216:219], v196 offset:39936
	global_load_lds_dwordx4 v[226:227], off
	v_lshl_add_u64 v[226:227], s[22:23], 0, v[138:139]
	s_mov_b32 m0, s51
	s_nop 0
	global_load_lds_dwordx4 v[226:227], off
	s_waitcnt vmcnt(8)
	s_waitcnt lgkmcnt(0)
	s_barrier
	v_mfma_f32_16x16x32_bf16 v[126:129], v[132:135], v[178:181], v[126:129]
	v_mfma_f32_16x16x32_bf16 v[122:125], v[154:157], v[178:181], v[122:125]
	v_mfma_f32_16x16x32_bf16 v[110:113], v[132:135], v[186:189], v[110:113]
	v_mfma_f32_16x16x32_bf16 v[106:109], v[154:157], v[186:189], v[106:109]
	v_mfma_f32_16x16x32_bf16 v[94:97], v[132:135], v[202:205], v[94:97]
	v_mfma_f32_16x16x32_bf16 v[90:93], v[154:157], v[202:205], v[90:93]
	v_mfma_f32_16x16x32_bf16 v[78:81], v[132:135], v[210:213], v[78:81]
	v_mfma_f32_16x16x32_bf16 v[74:77], v[154:157], v[210:213], v[74:77]
	v_mfma_f32_16x16x32_bf16 v[126:129], v[150:153], v[182:185], v[126:129]
	v_mfma_f32_16x16x32_bf16 v[122:125], v[158:161], v[182:185], v[122:125]
	v_mfma_f32_16x16x32_bf16 v[110:113], v[150:153], v[198:201], v[110:113]
	v_mfma_f32_16x16x32_bf16 v[106:109], v[158:161], v[198:201], v[106:109]
	v_mfma_f32_16x16x32_bf16 v[94:97], v[150:153], v[206:209], v[94:97]
	v_mfma_f32_16x16x32_bf16 v[90:93], v[158:161], v[206:209], v[90:93]
	v_mfma_f32_16x16x32_bf16 v[78:81], v[150:153], v[216:219], v[78:81]
	v_mfma_f32_16x16x32_bf16 v[74:77], v[158:161], v[216:219], v[74:77]
	v_mfma_f32_16x16x32_bf16 v[118:121], v[162:165], v[178:181], v[118:121]
	v_mfma_f32_16x16x32_bf16 v[114:117], v[170:173], v[178:181], v[114:117]
	v_mfma_f32_16x16x32_bf16 v[102:105], v[162:165], v[186:189], v[102:105]
	v_mfma_f32_16x16x32_bf16 v[98:101], v[170:173], v[186:189], v[98:101]
	v_mfma_f32_16x16x32_bf16 v[86:89], v[162:165], v[202:205], v[86:89]
	v_mfma_f32_16x16x32_bf16 v[82:85], v[170:173], v[202:205], v[82:85]
	v_mfma_f32_16x16x32_bf16 v[70:73], v[162:165], v[210:213], v[70:73]
	v_mfma_f32_16x16x32_bf16 v[66:69], v[170:173], v[210:213], v[66:69]
	v_mfma_f32_16x16x32_bf16 v[118:121], v[166:169], v[182:185], v[118:121]
	v_mfma_f32_16x16x32_bf16 v[114:117], v[174:177], v[182:185], v[114:117]
	v_mfma_f32_16x16x32_bf16 v[102:105], v[166:169], v[198:201], v[102:105]
	v_mfma_f32_16x16x32_bf16 v[98:101], v[174:177], v[198:201], v[98:101]
	v_mfma_f32_16x16x32_bf16 v[86:89], v[166:169], v[206:209], v[86:89]
	v_mfma_f32_16x16x32_bf16 v[82:85], v[174:177], v[206:209], v[82:85]
	v_mfma_f32_16x16x32_bf16 v[70:73], v[166:169], v[216:219], v[70:73]
	v_mfma_f32_16x16x32_bf16 v[66:69], v[174:177], v[216:219], v[66:69]
	s_barrier
	s_add_i32 s22, s60, s30
	v_lshl_add_u64 v[190:191], v[190:191], 0, s[18:19]
	s_mov_b32 m0, s22
	ds_read_b128 v[178:181], v196 offset:49152
	ds_read_b128 v[182:185], v196 offset:50176
	ds_read_b128 v[186:189], v196 offset:51200
	ds_read_b128 v[198:201], v196 offset:52224
	ds_read_b128 v[202:205], v196 offset:53248
	ds_read_b128 v[206:209], v196 offset:54272
	ds_read_b128 v[210:213], v196 offset:55296
	ds_read_b128 v[216:219], v196 offset:56320
	global_load_lds_dwordx4 v[190:191], off
	s_add_i32 m0, s22, 0x2000
	s_add_u32 s22, s26, 0x2b0080
	v_lshl_add_u64 v[190:191], v[220:221], 0, s[18:19]
	s_addc_u32 s23, s27, 0
	s_add_i32 s26, s61, s30
	global_load_lds_dwordx4 v[190:191], off
	v_lshl_add_u64 v[190:191], s[22:23], 0, v[140:141]
	s_mov_b32 m0, s26
	s_nop 0
	global_load_lds_dwordx4 v[190:191], off
	v_lshl_add_u64 v[190:191], s[22:23], 0, v[136:137]
	s_add_i32 m0, s26, 0x2000
	s_nop 0
	global_load_lds_dwordx4 v[190:191], off
	v_lshl_add_u64 v[190:191], v[222:223], 0, s[18:19]
	s_mov_b32 m0, s52
	s_nop 0
	global_load_lds_dwordx4 v[190:191], off
	v_lshl_add_u64 v[190:191], v[224:225], 0, s[18:19]
	s_mov_b32 m0, s53
	s_nop 0
	global_load_lds_dwordx4 v[190:191], off
	s_waitcnt vmcnt(8)
	s_waitcnt lgkmcnt(0)
	s_barrier
	v_mfma_f32_16x16x32_bf16 v[62:65], v[132:135], v[178:181], v[62:65]
	v_mfma_f32_16x16x32_bf16 v[58:61], v[154:157], v[178:181], v[58:61]
	v_mfma_f32_16x16x32_bf16 v[46:49], v[132:135], v[186:189], v[46:49]
	v_mfma_f32_16x16x32_bf16 v[42:45], v[154:157], v[186:189], v[42:45]
	v_mfma_f32_16x16x32_bf16 v[30:33], v[132:135], v[202:205], v[30:33]
	v_mfma_f32_16x16x32_bf16 v[26:29], v[154:157], v[202:205], v[26:29]
	v_mfma_f32_16x16x32_bf16 v[14:17], v[132:135], v[210:213], v[14:17]
	v_mfma_f32_16x16x32_bf16 v[10:13], v[154:157], v[210:213], v[10:13]
	v_mfma_f32_16x16x32_bf16 v[62:65], v[150:153], v[182:185], v[62:65]
	v_mfma_f32_16x16x32_bf16 v[58:61], v[158:161], v[182:185], v[58:61]
	v_mfma_f32_16x16x32_bf16 v[46:49], v[150:153], v[198:201], v[46:49]
	v_mfma_f32_16x16x32_bf16 v[42:45], v[158:161], v[198:201], v[42:45]
	v_mfma_f32_16x16x32_bf16 v[30:33], v[150:153], v[206:209], v[30:33]
	v_mfma_f32_16x16x32_bf16 v[26:29], v[158:161], v[206:209], v[26:29]
	v_mfma_f32_16x16x32_bf16 v[14:17], v[150:153], v[216:219], v[14:17]
	v_mfma_f32_16x16x32_bf16 v[10:13], v[158:161], v[216:219], v[10:13]
	v_mfma_f32_16x16x32_bf16 v[54:57], v[162:165], v[178:181], v[54:57]
	v_mfma_f32_16x16x32_bf16 v[50:53], v[170:173], v[178:181], v[50:53]
	v_mfma_f32_16x16x32_bf16 v[38:41], v[162:165], v[186:189], v[38:41]
	v_mfma_f32_16x16x32_bf16 v[34:37], v[170:173], v[186:189], v[34:37]
	v_mfma_f32_16x16x32_bf16 v[22:25], v[162:165], v[202:205], v[22:25]
	v_mfma_f32_16x16x32_bf16 v[18:21], v[170:173], v[202:205], v[18:21]
	v_mfma_f32_16x16x32_bf16 v[6:9], v[162:165], v[210:213], v[6:9]
	v_mfma_f32_16x16x32_bf16 v[2:5], v[170:173], v[210:213], v[2:5]
	v_mfma_f32_16x16x32_bf16 v[54:57], v[166:169], v[182:185], v[54:57]
	v_mfma_f32_16x16x32_bf16 v[50:53], v[174:177], v[182:185], v[50:53]
	v_mfma_f32_16x16x32_bf16 v[38:41], v[166:169], v[198:201], v[38:41]
	v_mfma_f32_16x16x32_bf16 v[34:37], v[174:177], v[198:201], v[34:37]
	v_mfma_f32_16x16x32_bf16 v[22:25], v[166:169], v[206:209], v[22:25]
	v_mfma_f32_16x16x32_bf16 v[18:21], v[174:177], v[206:209], v[18:21]
	v_mfma_f32_16x16x32_bf16 v[6:9], v[166:169], v[216:219], v[6:9]
	v_mfma_f32_16x16x32_bf16 v[2:5], v[174:177], v[216:219], v[2:5]
	s_barrier
	s_add_i32 s59, s59, 2
	s_add_u32 s57, s57, 0x100
	s_addc_u32 s58, s58, 0
	s_cmpk_gt_u32 s59, 0xa9
	s_mov_b64 s[22:23], s[24:25]
	s_cbranch_scc0 .LBB0_1354
	s_and_b64 vcc, exec, s[46:47]
	s_cbranch_vccz .LBB0_1357
	s_barrier

.LBB0_1405:
	s_add_u32 s22, s16, 0x100
	s_addc_u32 s23, s17, 0
	s_add_i32 s54, 0, 0x10000
	s_cmpk_eq_i32 s53, 0xa8
	s_cselect_b32 s27, s3, s23
	s_cselect_b32 s26, s2, s22
	v_add_u32_e32 v148, s54, v152
	s_cselect_b32 s25, s13, s52
	s_cselect_b32 s24, s12, s51
	s_add_i32 s55, 0, 0x14000
	ds_read_b128 v[144:147], v148
	ds_read_b128 v[156:159], v148 offset:1024
	ds_read_b128 v[160:163], v148 offset:2048
	ds_read_b128 v[164:167], v148 offset:3072
	v_add_u32_e32 v148, s55, v152
	ds_read_b128 v[168:171], v148
	ds_read_b128 v[172:175], v148 offset:1024
	ds_read_b128 v[176:179], v148 offset:2048
	ds_read_b128 v[180:183], v148 offset:3072
	v_lshl_add_u64 v[148:149], s[16:17], 0, v[140:141]
	s_add_i32 m0, s29, 0xc000
	ds_read_b128 v[184:187], v154
	ds_read_b128 v[188:191], v154 offset:1024
	ds_read_b128 v[192:195], v154 offset:2048
	ds_read_b128 v[196:199], v154 offset:3072
	ds_read_b128 v[200:203], v154 offset:4096
	ds_read_b128 v[204:207], v154 offset:5120
	ds_read_b128 v[208:211], v154 offset:6144
	ds_read_b128 v[216:219], v154 offset:7168
	global_load_lds_dwordx4 v[148:149], off
	v_lshl_add_u64 v[148:149], s[16:17], 0, v[142:143]
	s_add_i32 m0, s29, 0xe000
	s_nop 0
	global_load_lds_dwordx4 v[148:149], off
	s_waitcnt vmcnt(8)
	s_waitcnt lgkmcnt(0)
	s_barrier
	v_mfma_f32_16x16x32_bf16 v[126:129], v[144:147], v[184:187], v[126:129]
	v_mfma_f32_16x16x32_bf16 v[122:125], v[160:163], v[184:187], v[122:125]
	v_mfma_f32_16x16x32_bf16 v[110:113], v[144:147], v[192:195], v[110:113]
	v_mfma_f32_16x16x32_bf16 v[106:109], v[160:163], v[192:195], v[106:109]
	v_mfma_f32_16x16x32_bf16 v[94:97], v[144:147], v[200:203], v[94:97]
	v_mfma_f32_16x16x32_bf16 v[90:93], v[160:163], v[200:203], v[90:93]
	v_mfma_f32_16x16x32_bf16 v[78:81], v[144:147], v[208:211], v[78:81]
	v_mfma_f32_16x16x32_bf16 v[74:77], v[160:163], v[208:211], v[74:77]
	v_mfma_f32_16x16x32_bf16 v[126:129], v[156:159], v[188:191], v[126:129]
	v_mfma_f32_16x16x32_bf16 v[122:125], v[164:167], v[188:191], v[122:125]
	v_mfma_f32_16x16x32_bf16 v[110:113], v[156:159], v[196:199], v[110:113]
	v_mfma_f32_16x16x32_bf16 v[106:109], v[164:167], v[196:199], v[106:109]
	v_mfma_f32_16x16x32_bf16 v[94:97], v[156:159], v[204:207], v[94:97]
	v_mfma_f32_16x16x32_bf16 v[90:93], v[164:167], v[204:207], v[90:93]
	v_mfma_f32_16x16x32_bf16 v[78:81], v[156:159], v[216:219], v[78:81]
	v_mfma_f32_16x16x32_bf16 v[74:77], v[164:167], v[216:219], v[74:77]
	v_mfma_f32_16x16x32_bf16 v[118:121], v[168:171], v[184:187], v[118:121]
	v_mfma_f32_16x16x32_bf16 v[114:117], v[176:179], v[184:187], v[114:117]
	v_mfma_f32_16x16x32_bf16 v[102:105], v[168:171], v[192:195], v[102:105]
	v_mfma_f32_16x16x32_bf16 v[98:101], v[176:179], v[192:195], v[98:101]
	v_mfma_f32_16x16x32_bf16 v[86:89], v[168:171], v[200:203], v[86:89]
	v_mfma_f32_16x16x32_bf16 v[82:85], v[176:179], v[200:203], v[82:85]
	v_mfma_f32_16x16x32_bf16 v[70:73], v[168:171], v[208:211], v[70:73]
	v_mfma_f32_16x16x32_bf16 v[66:69], v[176:179], v[208:211], v[66:69]
	v_mfma_f32_16x16x32_bf16 v[118:121], v[172:175], v[188:191], v[118:121]
	v_mfma_f32_16x16x32_bf16 v[114:117], v[180:183], v[188:191], v[114:117]
	v_mfma_f32_16x16x32_bf16 v[102:105], v[172:175], v[196:199], v[102:105]
	v_mfma_f32_16x16x32_bf16 v[98:101], v[180:183], v[196:199], v[98:101]
	v_mfma_f32_16x16x32_bf16 v[86:89], v[172:175], v[204:207], v[86:89]
	v_mfma_f32_16x16x32_bf16 v[82:85], v[180:183], v[204:207], v[82:85]
	v_mfma_f32_16x16x32_bf16 v[70:73], v[172:175], v[216:219], v[70:73]
	v_mfma_f32_16x16x32_bf16 v[66:69], v[180:183], v[216:219], v[66:69]
	s_barrier
	s_add_i32 s16, s54, s28
	v_lshl_add_u64 v[148:149], s[24:25], 0, v[130:131]
	s_mov_b32 m0, s16
	ds_read_b128 v[184:187], v154 offset:16384
	ds_read_b128 v[188:191], v154 offset:17408
	ds_read_b128 v[192:195], v154 offset:18432
	ds_read_b128 v[196:199], v154 offset:19456
	ds_read_b128 v[200:203], v154 offset:20480
	ds_read_b128 v[204:207], v154 offset:21504
	ds_read_b128 v[208:211], v154 offset:22528
	ds_read_b128 v[216:219], v154 offset:23552
	global_load_lds_dwordx4 v[148:149], off
	s_add_i32 m0, s16, 0x2000
	s_add_u32 s16, s24, 0x2b0000
	v_lshl_add_u64 v[212:213], s[24:25], 0, v[132:133]
	s_addc_u32 s17, s25, 0
	s_add_i32 s54, s55, s28
	global_load_lds_dwordx4 v[212:213], off
	v_lshl_add_u64 v[220:221], s[16:17], 0, v[130:131]
	s_mov_b32 m0, s54
	v_lshl_add_u64 v[222:223], s[26:27], 0, v[134:135]
	global_load_lds_dwordx4 v[220:221], off
	v_lshl_add_u64 v[220:221], s[16:17], 0, v[132:133]
	s_add_i32 m0, s54, 0x2000
	s_nop 0
	global_load_lds_dwordx4 v[220:221], off
	v_lshl_add_u64 v[220:221], s[26:27], 0, v[136:137]
	s_mov_b32 m0, s29
	s_nop 0
	global_load_lds_dwordx4 v[220:221], off
	s_mov_b32 m0, s30
	s_nop 0
	global_load_lds_dwordx4 v[222:223], off
	s_waitcnt vmcnt(8)
	s_waitcnt lgkmcnt(0)
	s_barrier
	v_mfma_f32_16x16x32_bf16 v[62:65], v[144:147], v[184:187], v[62:65]
	v_mfma_f32_16x16x32_bf16 v[58:61], v[160:163], v[184:187], v[58:61]
	v_mfma_f32_16x16x32_bf16 v[46:49], v[144:147], v[192:195], v[46:49]
	v_mfma_f32_16x16x32_bf16 v[42:45], v[160:163], v[192:195], v[42:45]
	v_mfma_f32_16x16x32_bf16 v[30:33], v[144:147], v[200:203], v[30:33]
	v_mfma_f32_16x16x32_bf16 v[26:29], v[160:163], v[200:203], v[26:29]
	v_mfma_f32_16x16x32_bf16 v[14:17], v[144:147], v[208:211], v[14:17]
	v_mfma_f32_16x16x32_bf16 v[10:13], v[160:163], v[208:211], v[10:13]
	v_mfma_f32_16x16x32_bf16 v[62:65], v[156:159], v[188:191], v[62:65]
	v_mfma_f32_16x16x32_bf16 v[58:61], v[164:167], v[188:191], v[58:61]
	v_mfma_f32_16x16x32_bf16 v[46:49], v[156:159], v[196:199], v[46:49]
	v_mfma_f32_16x16x32_bf16 v[42:45], v[164:167], v[196:199], v[42:45]
	v_mfma_f32_16x16x32_bf16 v[30:33], v[156:159], v[204:207], v[30:33]
	v_mfma_f32_16x16x32_bf16 v[26:29], v[164:167], v[204:207], v[26:29]
	v_mfma_f32_16x16x32_bf16 v[14:17], v[156:159], v[216:219], v[14:17]
	v_mfma_f32_16x16x32_bf16 v[10:13], v[164:167], v[216:219], v[10:13]
	v_mfma_f32_16x16x32_bf16 v[54:57], v[168:171], v[184:187], v[54:57]
	v_mfma_f32_16x16x32_bf16 v[50:53], v[176:179], v[184:187], v[50:53]
	v_mfma_f32_16x16x32_bf16 v[38:41], v[168:171], v[192:195], v[38:41]
	v_mfma_f32_16x16x32_bf16 v[34:37], v[176:179], v[192:195], v[34:37]
	v_mfma_f32_16x16x32_bf16 v[22:25], v[168:171], v[200:203], v[22:25]
	v_mfma_f32_16x16x32_bf16 v[18:21], v[176:179], v[200:203], v[18:21]
	v_mfma_f32_16x16x32_bf16 v[6:9], v[168:171], v[208:211], v[6:9]
	v_mfma_f32_16x16x32_bf16 v[2:5], v[176:179], v[208:211], v[2:5]
	v_mfma_f32_16x16x32_bf16 v[54:57], v[172:175], v[188:191], v[54:57]
	v_mfma_f32_16x16x32_bf16 v[50:53], v[180:183], v[188:191], v[50:53]
	v_mfma_f32_16x16x32_bf16 v[38:41], v[172:175], v[196:199], v[38:41]
	v_mfma_f32_16x16x32_bf16 v[34:37], v[180:183], v[196:199], v[34:37]
	v_mfma_f32_16x16x32_bf16 v[22:25], v[172:175], v[204:207], v[22:25]
	v_mfma_f32_16x16x32_bf16 v[18:21], v[180:183], v[204:207], v[18:21]
	v_mfma_f32_16x16x32_bf16 v[6:9], v[172:175], v[216:219], v[6:9]
	v_mfma_f32_16x16x32_bf16 v[2:5], v[180:183], v[216:219], v[2:5]
	s_barrier
	s_add_i32 s54, 0, 0x18000
	v_add_u32_e32 v155, s54, v152
	s_add_i32 s55, 0, 0x1c000
	ds_read_b128 v[144:147], v155
	ds_read_b128 v[156:159], v155 offset:1024
	ds_read_b128 v[160:163], v155 offset:2048
	ds_read_b128 v[164:167], v155 offset:3072
	v_add_u32_e32 v155, s55, v152
	ds_read_b128 v[168:171], v155
	ds_read_b128 v[172:175], v155 offset:1024
	ds_read_b128 v[176:179], v155 offset:2048
	ds_read_b128 v[180:183], v155 offset:3072
	s_add_u32 s16, s26, 0x2b0000
	s_addc_u32 s17, s27, 0
	s_mov_b32 m0, s40
	v_lshl_add_u64 v[224:225], s[16:17], 0, v[136:137]
	ds_read_b128 v[184:187], v154 offset:32768
	ds_read_b128 v[188:191], v154 offset:33792
	ds_read_b128 v[192:195], v154 offset:34816
	ds_read_b128 v[196:199], v154 offset:35840
	ds_read_b128 v[200:203], v154 offset:36864
	ds_read_b128 v[204:207], v154 offset:37888
	ds_read_b128 v[208:211], v154 offset:38912
	ds_read_b128 v[216:219], v154 offset:39936
	global_load_lds_dwordx4 v[224:225], off
	v_lshl_add_u64 v[224:225], s[16:17], 0, v[134:135]
	s_mov_b32 m0, s41
	s_nop 0
	global_load_lds_dwordx4 v[224:225], off
	s_waitcnt vmcnt(8)
	s_waitcnt lgkmcnt(0)
	s_barrier
	v_mfma_f32_16x16x32_bf16 v[126:129], v[144:147], v[184:187], v[126:129]
	v_mfma_f32_16x16x32_bf16 v[122:125], v[160:163], v[184:187], v[122:125]
	v_mfma_f32_16x16x32_bf16 v[110:113], v[144:147], v[192:195], v[110:113]
	v_mfma_f32_16x16x32_bf16 v[106:109], v[160:163], v[192:195], v[106:109]
	v_mfma_f32_16x16x32_bf16 v[94:97], v[144:147], v[200:203], v[94:97]
	v_mfma_f32_16x16x32_bf16 v[90:93], v[160:163], v[200:203], v[90:93]
	v_mfma_f32_16x16x32_bf16 v[78:81], v[144:147], v[208:211], v[78:81]
	v_mfma_f32_16x16x32_bf16 v[74:77], v[160:163], v[208:211], v[74:77]
	v_mfma_f32_16x16x32_bf16 v[126:129], v[156:159], v[188:191], v[126:129]
	v_mfma_f32_16x16x32_bf16 v[122:125], v[164:167], v[188:191], v[122:125]
	v_mfma_f32_16x16x32_bf16 v[110:113], v[156:159], v[196:199], v[110:113]
	v_mfma_f32_16x16x32_bf16 v[106:109], v[164:167], v[196:199], v[106:109]
	v_mfma_f32_16x16x32_bf16 v[94:97], v[156:159], v[204:207], v[94:97]
	v_mfma_f32_16x16x32_bf16 v[90:93], v[164:167], v[204:207], v[90:93]
	v_mfma_f32_16x16x32_bf16 v[78:81], v[156:159], v[216:219], v[78:81]
	v_mfma_f32_16x16x32_bf16 v[74:77], v[164:167], v[216:219], v[74:77]
	v_mfma_f32_16x16x32_bf16 v[118:121], v[168:171], v[184:187], v[118:121]
	v_mfma_f32_16x16x32_bf16 v[114:117], v[176:179], v[184:187], v[114:117]
	v_mfma_f32_16x16x32_bf16 v[102:105], v[168:171], v[192:195], v[102:105]
	v_mfma_f32_16x16x32_bf16 v[98:101], v[176:179], v[192:195], v[98:101]
	v_mfma_f32_16x16x32_bf16 v[86:89], v[168:171], v[200:203], v[86:89]
	v_mfma_f32_16x16x32_bf16 v[82:85], v[176:179], v[200:203], v[82:85]
	v_mfma_f32_16x16x32_bf16 v[70:73], v[168:171], v[208:211], v[70:73]
	v_mfma_f32_16x16x32_bf16 v[66:69], v[176:179], v[208:211], v[66:69]
	v_mfma_f32_16x16x32_bf16 v[118:121], v[172:175], v[188:191], v[118:121]
	v_mfma_f32_16x16x32_bf16 v[114:117], v[180:183], v[188:191], v[114:117]
	v_mfma_f32_16x16x32_bf16 v[102:105], v[172:175], v[196:199], v[102:105]
	v_mfma_f32_16x16x32_bf16 v[98:101], v[180:183], v[196:199], v[98:101]
	v_mfma_f32_16x16x32_bf16 v[86:89], v[172:175], v[204:207], v[86:89]
	v_mfma_f32_16x16x32_bf16 v[82:85], v[180:183], v[204:207], v[82:85]
	v_mfma_f32_16x16x32_bf16 v[70:73], v[172:175], v[216:219], v[70:73]
	v_mfma_f32_16x16x32_bf16 v[66:69], v[180:183], v[216:219], v[66:69]
	s_barrier
	s_add_i32 s16, s54, s28
	v_lshl_add_u64 v[148:149], v[148:149], 0, s[18:19]
	s_mov_b32 m0, s16
	ds_read_b128 v[184:187], v154 offset:49152
	ds_read_b128 v[188:191], v154 offset:50176
	ds_read_b128 v[192:195], v154 offset:51200
	ds_read_b128 v[196:199], v154 offset:52224
	ds_read_b128 v[200:203], v154 offset:53248
	ds_read_b128 v[204:207], v154 offset:54272
	ds_read_b128 v[208:211], v154 offset:55296
	ds_read_b128 v[216:219], v154 offset:56320
	global_load_lds_dwordx4 v[148:149], off
	s_add_i32 m0, s16, 0x2000
	s_add_u32 s16, s24, 0x2b0080
	v_lshl_add_u64 v[148:149], v[212:213], 0, s[18:19]
	s_addc_u32 s17, s25, 0
	s_add_i32 s24, s55, s28
	global_load_lds_dwordx4 v[148:149], off
	v_lshl_add_u64 v[148:149], s[16:17], 0, v[130:131]
	s_mov_b32 m0, s24
	s_nop 0
	global_load_lds_dwordx4 v[148:149], off
	v_lshl_add_u64 v[148:149], s[16:17], 0, v[132:133]
	s_add_i32 m0, s24, 0x2000
	s_nop 0
	global_load_lds_dwordx4 v[148:149], off
	v_lshl_add_u64 v[148:149], v[220:221], 0, s[18:19]
	s_mov_b32 m0, s44
	s_nop 0
	global_load_lds_dwordx4 v[148:149], off
	v_lshl_add_u64 v[148:149], v[222:223], 0, s[18:19]
	s_mov_b32 m0, s45
	s_nop 0
	global_load_lds_dwordx4 v[148:149], off
	s_waitcnt vmcnt(8)
	s_waitcnt lgkmcnt(0)
	s_barrier
	v_mfma_f32_16x16x32_bf16 v[62:65], v[144:147], v[184:187], v[62:65]
	v_mfma_f32_16x16x32_bf16 v[58:61], v[160:163], v[184:187], v[58:61]
	v_mfma_f32_16x16x32_bf16 v[46:49], v[144:147], v[192:195], v[46:49]
	v_mfma_f32_16x16x32_bf16 v[42:45], v[160:163], v[192:195], v[42:45]
	v_mfma_f32_16x16x32_bf16 v[30:33], v[144:147], v[200:203], v[30:33]
	v_mfma_f32_16x16x32_bf16 v[26:29], v[160:163], v[200:203], v[26:29]
	v_mfma_f32_16x16x32_bf16 v[14:17], v[144:147], v[208:211], v[14:17]
	v_mfma_f32_16x16x32_bf16 v[10:13], v[160:163], v[208:211], v[10:13]
	v_mfma_f32_16x16x32_bf16 v[62:65], v[156:159], v[188:191], v[62:65]
	v_mfma_f32_16x16x32_bf16 v[58:61], v[164:167], v[188:191], v[58:61]
	v_mfma_f32_16x16x32_bf16 v[46:49], v[156:159], v[196:199], v[46:49]
	v_mfma_f32_16x16x32_bf16 v[42:45], v[164:167], v[196:199], v[42:45]
	v_mfma_f32_16x16x32_bf16 v[30:33], v[156:159], v[204:207], v[30:33]
	v_mfma_f32_16x16x32_bf16 v[26:29], v[164:167], v[204:207], v[26:29]
	v_mfma_f32_16x16x32_bf16 v[14:17], v[156:159], v[216:219], v[14:17]
	v_mfma_f32_16x16x32_bf16 v[10:13], v[164:167], v[216:219], v[10:13]
	v_mfma_f32_16x16x32_bf16 v[54:57], v[168:171], v[184:187], v[54:57]
	v_mfma_f32_16x16x32_bf16 v[50:53], v[176:179], v[184:187], v[50:53]
	v_mfma_f32_16x16x32_bf16 v[38:41], v[168:171], v[192:195], v[38:41]
	v_mfma_f32_16x16x32_bf16 v[34:37], v[176:179], v[192:195], v[34:37]
	v_mfma_f32_16x16x32_bf16 v[22:25], v[168:171], v[200:203], v[22:25]
	v_mfma_f32_16x16x32_bf16 v[18:21], v[176:179], v[200:203], v[18:21]
	v_mfma_f32_16x16x32_bf16 v[6:9], v[168:171], v[208:211], v[6:9]
	v_mfma_f32_16x16x32_bf16 v[2:5], v[176:179], v[208:211], v[2:5]
	v_mfma_f32_16x16x32_bf16 v[54:57], v[172:175], v[188:191], v[54:57]
	v_mfma_f32_16x16x32_bf16 v[50:53], v[180:183], v[188:191], v[50:53]
	v_mfma_f32_16x16x32_bf16 v[38:41], v[172:175], v[196:199], v[38:41]
	v_mfma_f32_16x16x32_bf16 v[34:37], v[180:183], v[196:199], v[34:37]
	v_mfma_f32_16x16x32_bf16 v[22:25], v[172:175], v[204:207], v[22:25]
	v_mfma_f32_16x16x32_bf16 v[18:21], v[180:183], v[204:207], v[18:21]
	v_mfma_f32_16x16x32_bf16 v[6:9], v[172:175], v[216:219], v[6:9]
	v_mfma_f32_16x16x32_bf16 v[2:5], v[180:183], v[216:219], v[2:5]
	s_barrier
	s_add_i32 s53, s53, 2
	s_add_u32 s51, s51, 0x100
	s_addc_u32 s52, s52, 0
	s_cmpk_gt_u32 s53, 0xa9
	s_mov_b64 s[16:17], s[22:23]
	s_cbranch_scc0 .LBB0_1405
	s_and_b64 vcc, exec, s[6:7]
	s_cbranch_vccz .LBB0_1408
	s_barrier
